# nt cache hint on once-read input streams: P0 cache f32 conversion loads, weight transpose loads, ada weight rows (LDS-DMA), P1 x rows
# speedup vs baseline: 1.0127x; 1.0021x over previous
.Lmy_ada_pf0:
	v_add_co_u32_e32 v138, vcc, 0x6000, v136
	s_add_i32 m0, s98, s100
	s_nop 0
	v_addc_co_u32_e32 v139, vcc, 0, v137, vcc
	global_load_lds_dword v[136:137], off nt
	s_add_i32 m0, m0, 0x100
	s_nop 0
	global_load_lds_dword v[138:139], off nt
	v_add_co_u32_e32 v136, vcc, 0xc000, v136
	s_nop 1
	v_addc_co_u32_e32 v137, vcc, 0, v137, vcc
	s_addk_i32 s100, 0x200
	s_cmpk_lg_i32 s100, 0x1000
	s_cbranch_scc1 .Lmy_ada_pf0
	s_mov_b32 s99, 0
.LBB0_12:
	s_cmpk_lt_i32 s45, 0x1e00
	s_cbranch_scc0 .Lmy_ada_tail0
	v_add_co_u32_e32 v136, vcc, 0x60000, v48
	s_add_i32 m0, s98, s100
	s_nop 0
	v_addc_co_u32_e32 v137, vcc, 0, v49, vcc
	v_add_co_u32_e32 v138, vcc, 0x66000, v48
	global_load_lds_dword v[136:137], off nt
	s_add_i32 m0, m0, 0x100
	v_addc_co_u32_e32 v139, vcc, 0, v49, vcc
	global_load_lds_dword v[138:139], off nt
	s_waitcnt vmcnt(16)
	s_branch .Lmy_ada_go0

.Lmy_ada_pf1:
	v_add_co_u32_e32 v136, vcc, s54, v138
	s_add_i32 m0, s98, s100
	s_nop 0
	v_addc_co_u32_e32 v137, vcc, -1, v139, vcc
	s_nop 0
	global_load_lds_dword v[136:137], off nt
	s_add_i32 m0, m0, 0x100
	s_nop 0
	global_load_lds_dword v[138:139], off nt
	v_add_co_u32_e32 v138, vcc, 0xc000, v138
	s_nop 1
	v_addc_co_u32_e32 v139, vcc, 0, v139, vcc
	s_addk_i32 s100, 0x200
	s_cmpk_lg_i32 s100, 0x1000
	s_cbranch_scc1 .Lmy_ada_pf1
	s_mov_b32 s99, 0
.LBB0_16:
	s_cmpk_lt_i32 s45, 0x1e00
	s_cbranch_scc0 .Lmy_ada_tail1
	v_add_co_u32_e32 v136, vcc, 0x5a000, v46
	s_add_i32 m0, s98, s100
	s_nop 0
	v_addc_co_u32_e32 v137, vcc, 0, v47, vcc
	v_add_co_u32_e32 v138, vcc, 0x60000, v46
	global_load_lds_dword v[136:137], off nt
	s_add_i32 m0, m0, 0x100
	v_addc_co_u32_e32 v139, vcc, 0, v47, vcc
	global_load_lds_dword v[138:139], off nt
	s_waitcnt vmcnt(16)
	s_branch .Lmy_ada_go1

.LBB0_33:
	s_lshl_b32 s49, s21, 1
	s_lshl_b32 s50, s29, 1
	v_or_b32_e32 v67, s50, v4
	s_add_i32 s51, s49, 4
	s_add_i32 s52, s50, 4
	s_add_i32 s54, s50, 8
	v_add_u32_e32 v8, s17, v67
	v_or_b32_e32 v68, s51, v1
	v_or_b32_e32 v69, s52, v4
	v_mov_b32_e32 v47, v9
	v_or_b32_e32 v66, s49, v1
	s_add_i32 s56, s50, 12
	v_or_b32_e32 v71, s54, v4
	v_lshlrev_b64 v[60:61], 12, v[8:9]
	v_add_u32_e32 v46, s26, v68
	v_add_u32_e32 v8, s17, v69
	v_mov_b32_e32 v45, v9
	s_add_i32 s53, s49, 8
	s_add_i32 s55, s49, 12
	s_add_i32 s58, s50, 16
	v_add_u32_e32 v44, s26, v66
	v_or_b32_e32 v73, s56, v4
	v_lshlrev_b64 v[46:47], 12, v[46:47]
	v_lshlrev_b64 v[62:63], 12, v[8:9]
	v_add_u32_e32 v8, s17, v71
	s_add_i32 s60, s50, 20
	v_or_b32_e32 v70, s53, v1
	v_or_b32_e32 v72, s55, v1
	v_or_b32_e32 v75, s58, v4
	v_lshlrev_b64 v[44:45], 12, v[44:45]
	v_lshl_add_u64 v[60:61], v[42:43], 0, v[60:61]
	v_lshl_add_u64 v[46:47], v[42:43], 0, v[46:47]
	v_lshlrev_b64 v[64:65], 12, v[8:9]
	v_add_u32_e32 v8, s17, v73
	v_mov_b32_e32 v49, v9
	v_mov_b32_e32 v51, v9
	s_add_i32 s57, s49, 16
	s_add_i32 s59, s49, 20
	s_add_i32 s62, s50, 24
	v_or_b32_e32 v77, s60, v4
	v_add_u32_e32 v48, s26, v70
	v_add_u32_e32 v50, s26, v72
	v_lshl_add_u64 v[44:45], v[42:43], 0, v[44:45]
	v_lshl_add_u64 v[62:63], v[42:43], 0, v[62:63]
	global_load_dword v82, v[60:61], off nt
	global_load_dword v83, v[44:45], off nt
	global_load_dword v84, v[62:63], off nt
	global_load_dword v85, v[46:47], off nt
	v_lshlrev_b64 v[46:47], 12, v[8:9]
	v_add_u32_e32 v8, s17, v75
	s_add_i32 s61, s49, 24
	s_add_i32 s49, s49, 28
	s_add_i32 s50, s50, 28
	v_or_b32_e32 v74, s57, v1
	v_or_b32_e32 v76, s59, v1
	v_or_b32_e32 v79, s62, v4
	v_lshlrev_b64 v[48:49], 12, v[48:49]
	v_lshlrev_b64 v[50:51], 12, v[50:51]
	v_lshl_add_u64 v[44:45], v[42:43], 0, v[64:65]
	v_lshl_add_u64 v[46:47], v[42:43], 0, v[46:47]
	v_lshlrev_b64 v[60:61], 12, v[8:9]
	v_add_u32_e32 v8, s17, v77
	v_mov_b32_e32 v53, v9
	v_mov_b32_e32 v55, v9
	v_or_b32_e32 v78, s61, v1
	v_or_b32_e32 v80, s49, v1
	v_or_b32_e32 v81, s50, v4
	v_add_u32_e32 v52, s26, v74
	v_add_u32_e32 v54, s26, v76
	v_lshl_add_u64 v[48:49], v[42:43], 0, v[48:49]
	v_lshl_add_u64 v[50:51], v[42:43], 0, v[50:51]
	global_load_dword v86, v[44:45], off nt
	global_load_dword v87, v[48:49], off nt
	global_load_dword v88, v[46:47], off nt
	global_load_dword v89, v[50:51], off nt
	v_lshlrev_b64 v[46:47], 12, v[8:9]
	v_add_u32_e32 v8, s17, v79
	v_mov_b32_e32 v57, v9
	v_mov_b32_e32 v59, v9
	v_add_u32_e32 v56, s26, v78
	v_add_u32_e32 v58, s26, v80
	v_lshlrev_b64 v[52:53], 12, v[52:53]
	v_lshlrev_b64 v[54:55], 12, v[54:55]
	v_lshl_add_u64 v[44:45], v[42:43], 0, v[60:61]
	v_lshl_add_u64 v[46:47], v[42:43], 0, v[46:47]
	v_lshlrev_b64 v[48:49], 12, v[8:9]
	v_add_u32_e32 v8, s17, v81
	v_lshlrev_b64 v[56:57], 12, v[56:57]
	v_lshlrev_b64 v[58:59], 12, v[58:59]
	v_lshl_add_u64 v[52:53], v[42:43], 0, v[52:53]
	v_lshl_add_u64 v[54:55], v[42:43], 0, v[54:55]
	global_load_dword v90, v[44:45], off nt
	global_load_dword v91, v[52:53], off nt
	global_load_dword v92, v[46:47], off nt
	global_load_dword v93, v[54:55], off nt
	v_lshl_add_u64 v[44:45], v[42:43], 0, v[48:49]
	v_lshlrev_b64 v[46:47], 12, v[8:9]
	v_lshl_add_u64 v[56:57], v[42:43], 0, v[56:57]
	v_lshl_add_u64 v[58:59], v[42:43], 0, v[58:59]
	v_lshl_add_u64 v[46:47], v[42:43], 0, v[46:47]
	global_load_dword v8, v[44:45], off nt
	global_load_dword v94, v[56:57], off nt
	global_load_dword v95, v[46:47], off nt
	global_load_dword v96, v[58:59], off nt
	s_add_i32 s29, s29, 16
	s_add_i32 s21, s21, 16
	s_add_i32 s48, s48, -16
	v_mad_u64_u32 v[44:45], s[50:51], v67, s47, v[10:11]
	s_cmp_lg_u32 s48, 0
	v_mad_u64_u32 v[46:47], s[50:51], v66, s47, v[10:11]
	v_mad_u64_u32 v[48:49], s[50:51], v69, s47, v[10:11]
	v_mad_u64_u32 v[50:51], s[50:51], v68, s47, v[10:11]
	v_mad_u64_u32 v[52:53], s[50:51], v71, s47, v[10:11]
	v_mad_u64_u32 v[54:55], s[50:51], v70, s47, v[10:11]
	v_mad_u64_u32 v[56:57], s[50:51], v73, s47, v[10:11]
	v_mad_u64_u32 v[58:59], s[50:51], v72, s47, v[10:11]
	v_mad_u64_u32 v[60:61], s[50:51], v75, s47, v[10:11]
	v_mad_u64_u32 v[62:63], s[50:51], v74, s47, v[10:11]
	v_mad_u64_u32 v[64:65], s[50:51], v77, s47, v[10:11]
	v_mad_u64_u32 v[66:67], s[50:51], v76, s47, v[10:11]
	v_mad_u64_u32 v[68:69], s[50:51], v79, s47, v[10:11]
	v_mad_u64_u32 v[70:71], s[50:51], v78, s47, v[10:11]
	v_mad_u64_u32 v[72:73], s[50:51], v81, s47, v[10:11]
	v_mad_u64_u32 v[74:75], s[50:51], v80, s47, v[10:11]
	s_waitcnt vmcnt(15)
	ds_write_b32 v44, v82
	s_waitcnt vmcnt(14)
	ds_write_b32 v46, v83
	s_waitcnt vmcnt(13)
	ds_write_b32 v48, v84
	s_waitcnt vmcnt(12)
	ds_write_b32 v50, v85
	s_waitcnt vmcnt(11)
	ds_write_b32 v52, v86
	s_waitcnt vmcnt(10)
	ds_write_b32 v54, v87
	s_waitcnt vmcnt(9)
	ds_write_b32 v56, v88
	s_waitcnt vmcnt(8)
	ds_write_b32 v58, v89
	s_waitcnt vmcnt(7)
	ds_write_b32 v60, v90
	s_waitcnt vmcnt(6)
	ds_write_b32 v62, v91
	s_waitcnt vmcnt(5)
	ds_write_b32 v64, v92
	s_waitcnt vmcnt(4)
	ds_write_b32 v66, v93
	s_waitcnt vmcnt(3)
	ds_write_b32 v68, v8
	s_waitcnt vmcnt(2)
	ds_write_b32 v70, v94
	s_waitcnt vmcnt(1)
	ds_write_b32 v72, v95
	s_waitcnt vmcnt(0)
	ds_write_b32 v74, v96
	s_cbranch_scc1 .LBB0_33
	s_waitcnt lgkmcnt(0)
	ds_read2_b32 v[46:47], v5 offset0:33 offset1:41
	ds_read2_b32 v[48:49], v5 offset1:8
	ds_read2_b32 v[50:51], v5 offset0:66 offset1:74
	ds_read2_b32 v[52:53], v5 offset0:99 offset1:107
	ds_read2_b32 v[54:55], v5 offset0:132 offset1:140
	ds_read2_b32 v[56:57], v5 offset0:165 offset1:173
	ds_read2_b32 v[58:59], v5 offset0:198 offset1:206
	ds_read2_b32 v[60:61], v5 offset0:231 offset1:239
	s_lshl_b32 s26, s17, 1
	v_or_b32_e32 v8, s16, v3
	v_lshl_add_u64 v[62:63], v[14:15], 0, s[26:27]
	v_lshlrev_b32_e32 v8, 11, v8
	s_waitcnt lgkmcnt(6)
	v_cvt_pk_bf16_f32 v42, v48, v46
	s_waitcnt lgkmcnt(4)
	v_cvt_pk_bf16_f32 v43, v50, v52
	s_waitcnt lgkmcnt(2)
	v_cvt_pk_bf16_f32 v44, v54, v56
	s_waitcnt lgkmcnt(0)
	v_cvt_pk_bf16_f32 v45, v58, v60
	v_lshl_add_u64 v[64:65], v[62:63], 0, v[8:9]
	global_store_dwordx4 v[64:65], v[42:45], off
	v_or_b32_e32 v8, s16, v7
	v_lshlrev_b32_e32 v8, 11, v8
	v_cvt_pk_bf16_f32 v42, v49, v47
	v_cvt_pk_bf16_f32 v43, v51, v53
	v_cvt_pk_bf16_f32 v44, v55, v57
	v_cvt_pk_bf16_f32 v45, v59, v61
	ds_read2_b32 v[48:49], v5 offset0:49 offset1:57
	ds_read2_b32 v[50:51], v5 offset0:16 offset1:24
	ds_read2_b32 v[52:53], v5 offset0:82 offset1:90
	ds_read2_b32 v[54:55], v5 offset0:115 offset1:123
	ds_read2_b32 v[56:57], v5 offset0:148 offset1:156
	ds_read2_b32 v[58:59], v5 offset0:181 offset1:189
	ds_read2_b32 v[60:61], v5 offset0:214 offset1:222
	ds_read2_b32 v[64:65], v5 offset0:247 offset1:255
	v_lshl_add_u64 v[46:47], v[62:63], 0, v[8:9]
	v_or_b32_e32 v8, s16, v11
	v_lshlrev_b32_e32 v8, 11, v8
	global_store_dwordx4 v[46:47], v[42:45], off
	v_lshl_add_u64 v[46:47], v[62:63], 0, v[8:9]
	v_or_b32_e32 v8, s16, v13
	s_waitcnt lgkmcnt(6)
	v_cvt_pk_bf16_f32 v42, v50, v48
	s_waitcnt lgkmcnt(4)
	v_cvt_pk_bf16_f32 v43, v52, v54
	s_waitcnt lgkmcnt(2)
	v_cvt_pk_bf16_f32 v44, v56, v58
	s_waitcnt lgkmcnt(0)
	v_cvt_pk_bf16_f32 v45, v60, v64
	v_lshlrev_b32_e32 v8, 11, v8
	global_store_dwordx4 v[46:47], v[42:45], off
	v_lshl_add_u64 v[46:47], v[62:63], 0, v[8:9]
	s_mov_b64 s[16:17], 0
	v_cvt_pk_bf16_f32 v42, v51, v49
	v_cvt_pk_bf16_f32 v43, v53, v55
	v_cvt_pk_bf16_f32 v44, v57, v59
	v_cvt_pk_bf16_f32 v45, v61, v65
	global_store_dwordx4 v[46:47], v[42:45], off
	s_waitcnt lgkmcnt(0)

.LBB0_37:
	s_lshl_b32 s48, s21, 1
	s_lshl_b32 s49, s26, 1
	v_or_b32_e32 v67, s49, v4
	s_add_i32 s50, s48, 4
	s_add_i32 s51, s49, 4
	s_add_i32 s53, s49, 8
	v_add_u32_e32 v8, s17, v67
	v_or_b32_e32 v68, s50, v1
	v_or_b32_e32 v69, s51, v4
	v_mov_b32_e32 v47, v9
	v_or_b32_e32 v66, s48, v1
	s_add_i32 s55, s49, 12
	v_or_b32_e32 v71, s53, v4
	v_lshlrev_b64 v[60:61], 13, v[8:9]
	v_add_u32_e32 v46, s20, v68
	v_add_u32_e32 v8, s17, v69
	v_mov_b32_e32 v45, v9
	s_add_i32 s52, s48, 8
	s_add_i32 s54, s48, 12
	s_add_i32 s57, s49, 16
	v_add_u32_e32 v44, s20, v66
	v_or_b32_e32 v73, s55, v4
	v_lshlrev_b64 v[46:47], 13, v[46:47]
	v_lshlrev_b64 v[62:63], 13, v[8:9]
	v_add_u32_e32 v8, s17, v71
	s_add_i32 s59, s49, 20
	v_or_b32_e32 v70, s52, v1
	v_or_b32_e32 v72, s54, v1
	v_or_b32_e32 v75, s57, v4
	v_lshlrev_b64 v[44:45], 13, v[44:45]
	v_lshl_add_u64 v[60:61], v[42:43], 0, v[60:61]
	v_lshl_add_u64 v[46:47], v[42:43], 0, v[46:47]
	v_lshlrev_b64 v[64:65], 13, v[8:9]
	v_add_u32_e32 v8, s17, v73
	v_mov_b32_e32 v49, v9
	v_mov_b32_e32 v51, v9
	s_add_i32 s56, s48, 16
	s_add_i32 s58, s48, 20
	s_add_i32 s61, s49, 24
	v_or_b32_e32 v77, s59, v4
	v_add_u32_e32 v48, s20, v70
	v_add_u32_e32 v50, s20, v72
	v_lshl_add_u64 v[44:45], v[42:43], 0, v[44:45]
	v_lshl_add_u64 v[62:63], v[42:43], 0, v[62:63]
	global_load_dword v82, v[60:61], off nt
	global_load_dword v83, v[44:45], off nt
	global_load_dword v84, v[62:63], off nt
	global_load_dword v85, v[46:47], off nt
	v_lshlrev_b64 v[46:47], 13, v[8:9]
	v_add_u32_e32 v8, s17, v75
	s_add_i32 s60, s48, 24
	s_add_i32 s48, s48, 28
	s_add_i32 s49, s49, 28
	v_or_b32_e32 v74, s56, v1
	v_or_b32_e32 v76, s58, v1
	v_or_b32_e32 v79, s61, v4
	v_lshlrev_b64 v[48:49], 13, v[48:49]
	v_lshlrev_b64 v[50:51], 13, v[50:51]
	v_lshl_add_u64 v[44:45], v[42:43], 0, v[64:65]
	v_lshl_add_u64 v[46:47], v[42:43], 0, v[46:47]
	v_lshlrev_b64 v[60:61], 13, v[8:9]
	v_add_u32_e32 v8, s17, v77
	v_mov_b32_e32 v53, v9
	v_mov_b32_e32 v55, v9
	v_or_b32_e32 v78, s60, v1
	v_or_b32_e32 v80, s48, v1
	v_or_b32_e32 v81, s49, v4
	v_add_u32_e32 v52, s20, v74
	v_add_u32_e32 v54, s20, v76
	v_lshl_add_u64 v[48:49], v[42:43], 0, v[48:49]
	v_lshl_add_u64 v[50:51], v[42:43], 0, v[50:51]
	global_load_dword v86, v[44:45], off nt
	global_load_dword v87, v[48:49], off nt
	global_load_dword v88, v[46:47], off nt
	global_load_dword v89, v[50:51], off nt
	v_lshlrev_b64 v[46:47], 13, v[8:9]
	v_add_u32_e32 v8, s17, v79
	v_mov_b32_e32 v57, v9
	v_mov_b32_e32 v59, v9
	v_add_u32_e32 v56, s20, v78
	v_add_u32_e32 v58, s20, v80
	v_lshlrev_b64 v[52:53], 13, v[52:53]
	v_lshlrev_b64 v[54:55], 13, v[54:55]
	v_lshl_add_u64 v[44:45], v[42:43], 0, v[60:61]
	v_lshl_add_u64 v[46:47], v[42:43], 0, v[46:47]
	v_lshlrev_b64 v[48:49], 13, v[8:9]
	v_add_u32_e32 v8, s17, v81
	v_lshlrev_b64 v[56:57], 13, v[56:57]
	v_lshlrev_b64 v[58:59], 13, v[58:59]
	v_lshl_add_u64 v[52:53], v[42:43], 0, v[52:53]
	v_lshl_add_u64 v[54:55], v[42:43], 0, v[54:55]
	global_load_dword v90, v[44:45], off nt
	global_load_dword v91, v[52:53], off nt
	global_load_dword v92, v[46:47], off nt
	global_load_dword v93, v[54:55], off nt
	v_lshl_add_u64 v[44:45], v[42:43], 0, v[48:49]
	v_lshlrev_b64 v[46:47], 13, v[8:9]
	v_lshl_add_u64 v[56:57], v[42:43], 0, v[56:57]
	v_lshl_add_u64 v[58:59], v[42:43], 0, v[58:59]
	v_lshl_add_u64 v[46:47], v[42:43], 0, v[46:47]
	global_load_dword v8, v[44:45], off nt
	global_load_dword v94, v[56:57], off nt
	global_load_dword v95, v[46:47], off nt
	global_load_dword v96, v[58:59], off nt
	s_add_i32 s26, s26, 16
	s_add_i32 s21, s21, 16
	s_add_i32 s29, s29, -16
	v_mad_u64_u32 v[44:45], s[48:49], v67, s47, v[10:11]
	s_cmp_lg_u32 s29, 0
	v_mad_u64_u32 v[46:47], s[48:49], v66, s47, v[10:11]
	v_mad_u64_u32 v[48:49], s[48:49], v69, s47, v[10:11]
	v_mad_u64_u32 v[50:51], s[48:49], v68, s47, v[10:11]
	v_mad_u64_u32 v[52:53], s[48:49], v71, s47, v[10:11]
	v_mad_u64_u32 v[54:55], s[48:49], v70, s47, v[10:11]
	v_mad_u64_u32 v[56:57], s[48:49], v73, s47, v[10:11]
	v_mad_u64_u32 v[58:59], s[48:49], v72, s47, v[10:11]
	v_mad_u64_u32 v[60:61], s[48:49], v75, s47, v[10:11]
	v_mad_u64_u32 v[62:63], s[48:49], v74, s47, v[10:11]
	v_mad_u64_u32 v[64:65], s[48:49], v77, s47, v[10:11]
	v_mad_u64_u32 v[66:67], s[48:49], v76, s47, v[10:11]
	v_mad_u64_u32 v[68:69], s[48:49], v79, s47, v[10:11]
	v_mad_u64_u32 v[70:71], s[48:49], v78, s47, v[10:11]
	v_mad_u64_u32 v[72:73], s[48:49], v81, s47, v[10:11]
	v_mad_u64_u32 v[74:75], s[48:49], v80, s47, v[10:11]
	s_waitcnt vmcnt(15)
	ds_write_b32 v44, v82
	s_waitcnt vmcnt(14)
	ds_write_b32 v46, v83
	s_waitcnt vmcnt(13)
	ds_write_b32 v48, v84
	s_waitcnt vmcnt(12)
	ds_write_b32 v50, v85
	s_waitcnt vmcnt(11)
	ds_write_b32 v52, v86
	s_waitcnt vmcnt(10)
	ds_write_b32 v54, v87
	s_waitcnt vmcnt(9)
	ds_write_b32 v56, v88
	s_waitcnt vmcnt(8)
	ds_write_b32 v58, v89
	s_waitcnt vmcnt(7)
	ds_write_b32 v60, v90
	s_waitcnt vmcnt(6)
	ds_write_b32 v62, v91
	s_waitcnt vmcnt(5)
	ds_write_b32 v64, v92
	s_waitcnt vmcnt(4)
	ds_write_b32 v66, v93
	s_waitcnt vmcnt(3)
	ds_write_b32 v68, v8
	s_waitcnt vmcnt(2)
	ds_write_b32 v70, v94
	s_waitcnt vmcnt(1)
	ds_write_b32 v72, v95
	s_waitcnt vmcnt(0)
	ds_write_b32 v74, v96
	s_cbranch_scc1 .LBB0_37
	s_waitcnt lgkmcnt(0)
	ds_read2_b32 v[46:47], v5 offset0:33 offset1:41
	ds_read2_b32 v[48:49], v5 offset1:8
	ds_read2_b32 v[50:51], v5 offset0:66 offset1:74
	ds_read2_b32 v[52:53], v5 offset0:99 offset1:107
	ds_read2_b32 v[54:55], v5 offset0:132 offset1:140
	ds_read2_b32 v[56:57], v5 offset0:165 offset1:173
	ds_read2_b32 v[58:59], v5 offset0:198 offset1:206
	ds_read2_b32 v[60:61], v5 offset0:231 offset1:239
	s_lshl_b32 s26, s17, 1
	v_or_b32_e32 v8, s16, v3
	v_lshl_add_u64 v[62:63], v[16:17], 0, s[26:27]
	v_lshlrev_b32_e32 v8, 11, v8
	s_waitcnt lgkmcnt(6)
	v_cvt_pk_bf16_f32 v42, v48, v46
	s_waitcnt lgkmcnt(4)
	v_cvt_pk_bf16_f32 v43, v50, v52
	s_waitcnt lgkmcnt(2)
	v_cvt_pk_bf16_f32 v44, v54, v56
	s_waitcnt lgkmcnt(0)
	v_cvt_pk_bf16_f32 v45, v58, v60
	v_lshl_add_u64 v[64:65], v[62:63], 0, v[8:9]
	global_store_dwordx4 v[64:65], v[42:45], off
	v_or_b32_e32 v8, s16, v7
	v_lshlrev_b32_e32 v8, 11, v8
	v_cvt_pk_bf16_f32 v42, v49, v47
	v_cvt_pk_bf16_f32 v43, v51, v53
	v_cvt_pk_bf16_f32 v44, v55, v57
	v_cvt_pk_bf16_f32 v45, v59, v61
	ds_read2_b32 v[48:49], v5 offset0:49 offset1:57
	ds_read2_b32 v[50:51], v5 offset0:16 offset1:24
	ds_read2_b32 v[52:53], v5 offset0:82 offset1:90
	ds_read2_b32 v[54:55], v5 offset0:115 offset1:123
	ds_read2_b32 v[56:57], v5 offset0:148 offset1:156
	ds_read2_b32 v[58:59], v5 offset0:181 offset1:189
	ds_read2_b32 v[60:61], v5 offset0:214 offset1:222
	ds_read2_b32 v[64:65], v5 offset0:247 offset1:255
	v_lshl_add_u64 v[46:47], v[62:63], 0, v[8:9]
	v_or_b32_e32 v8, s16, v11
	v_lshlrev_b32_e32 v8, 11, v8
	global_store_dwordx4 v[46:47], v[42:45], off
	v_lshl_add_u64 v[46:47], v[62:63], 0, v[8:9]
	v_or_b32_e32 v8, s16, v13
	s_waitcnt lgkmcnt(6)
	v_cvt_pk_bf16_f32 v42, v50, v48
	s_waitcnt lgkmcnt(4)
	v_cvt_pk_bf16_f32 v43, v52, v54
	s_waitcnt lgkmcnt(2)
	v_cvt_pk_bf16_f32 v44, v56, v58
	s_waitcnt lgkmcnt(0)
	v_cvt_pk_bf16_f32 v45, v60, v64
	v_lshlrev_b32_e32 v8, 11, v8
	global_store_dwordx4 v[46:47], v[42:45], off
	v_lshl_add_u64 v[46:47], v[62:63], 0, v[8:9]
	s_nop 0
	v_cvt_pk_bf16_f32 v42, v51, v49
	v_cvt_pk_bf16_f32 v43, v53, v55
	v_cvt_pk_bf16_f32 v44, v57, v59
	v_cvt_pk_bf16_f32 v45, v61, v65
	global_store_dwordx4 v[46:47], v[42:45], off
	s_waitcnt lgkmcnt(0)

.LBB0_42:
	s_lshl_b32 s49, s20, 1
	s_lshl_b32 s50, s29, 1
	v_or_b32_e32 v67, s50, v4
	s_add_i32 s51, s49, 4
	s_add_i32 s52, s50, 4
	s_add_i32 s54, s50, 8
	v_add_u32_e32 v8, s17, v67
	v_or_b32_e32 v68, s51, v1
	v_or_b32_e32 v69, s52, v4
	v_mov_b32_e32 v47, v9
	v_or_b32_e32 v66, s49, v1
	s_add_i32 s56, s50, 12
	v_or_b32_e32 v71, s54, v4
	v_lshlrev_b64 v[60:61], 12, v[8:9]
	v_add_u32_e32 v46, s21, v68
	v_add_u32_e32 v8, s17, v69
	v_mov_b32_e32 v45, v9
	s_add_i32 s53, s49, 8
	s_add_i32 s55, s49, 12
	s_add_i32 s58, s50, 16
	v_add_u32_e32 v44, s21, v66
	v_or_b32_e32 v73, s56, v4
	v_lshlrev_b64 v[46:47], 12, v[46:47]
	v_lshlrev_b64 v[62:63], 12, v[8:9]
	v_add_u32_e32 v8, s17, v71
	s_add_i32 s60, s50, 20
	v_or_b32_e32 v70, s53, v1
	v_or_b32_e32 v72, s55, v1
	v_or_b32_e32 v75, s58, v4
	v_lshlrev_b64 v[44:45], 12, v[44:45]
	v_lshl_add_u64 v[60:61], v[42:43], 0, v[60:61]
	v_lshl_add_u64 v[46:47], v[42:43], 0, v[46:47]
	v_lshlrev_b64 v[64:65], 12, v[8:9]
	v_add_u32_e32 v8, s17, v73
	v_mov_b32_e32 v49, v9
	v_mov_b32_e32 v51, v9
	s_add_i32 s57, s49, 16
	s_add_i32 s59, s49, 20
	s_add_i32 s62, s50, 24
	v_or_b32_e32 v77, s60, v4
	v_add_u32_e32 v48, s21, v70
	v_add_u32_e32 v50, s21, v72
	v_lshl_add_u64 v[44:45], v[42:43], 0, v[44:45]
	v_lshl_add_u64 v[62:63], v[42:43], 0, v[62:63]
	global_load_dword v82, v[60:61], off nt
	global_load_dword v83, v[44:45], off nt
	global_load_dword v84, v[62:63], off nt
	global_load_dword v85, v[46:47], off nt
	v_lshlrev_b64 v[46:47], 12, v[8:9]
	v_add_u32_e32 v8, s17, v75
	s_add_i32 s61, s49, 24
	s_add_i32 s49, s49, 28
	s_add_i32 s50, s50, 28
	v_or_b32_e32 v74, s57, v1
	v_or_b32_e32 v76, s59, v1
	v_or_b32_e32 v79, s62, v4
	v_lshlrev_b64 v[48:49], 12, v[48:49]
	v_lshlrev_b64 v[50:51], 12, v[50:51]
	v_lshl_add_u64 v[44:45], v[42:43], 0, v[64:65]
	v_lshl_add_u64 v[46:47], v[42:43], 0, v[46:47]
	v_lshlrev_b64 v[60:61], 12, v[8:9]
	v_add_u32_e32 v8, s17, v77
	v_mov_b32_e32 v53, v9
	v_mov_b32_e32 v55, v9
	v_or_b32_e32 v78, s61, v1
	v_or_b32_e32 v80, s49, v1
	v_or_b32_e32 v81, s50, v4
	v_add_u32_e32 v52, s21, v74
	v_add_u32_e32 v54, s21, v76
	v_lshl_add_u64 v[48:49], v[42:43], 0, v[48:49]
	v_lshl_add_u64 v[50:51], v[42:43], 0, v[50:51]
	global_load_dword v86, v[44:45], off nt
	global_load_dword v87, v[48:49], off nt
	global_load_dword v88, v[46:47], off nt
	global_load_dword v89, v[50:51], off nt
	v_lshlrev_b64 v[46:47], 12, v[8:9]
	v_add_u32_e32 v8, s17, v79
	v_mov_b32_e32 v57, v9
	v_mov_b32_e32 v59, v9
	v_add_u32_e32 v56, s21, v78
	v_add_u32_e32 v58, s21, v80
	v_lshlrev_b64 v[52:53], 12, v[52:53]
	v_lshlrev_b64 v[54:55], 12, v[54:55]
	v_lshl_add_u64 v[44:45], v[42:43], 0, v[60:61]
	v_lshl_add_u64 v[46:47], v[42:43], 0, v[46:47]
	v_lshlrev_b64 v[48:49], 12, v[8:9]
	v_add_u32_e32 v8, s17, v81
	v_lshlrev_b64 v[56:57], 12, v[56:57]
	v_lshlrev_b64 v[58:59], 12, v[58:59]
	v_lshl_add_u64 v[52:53], v[42:43], 0, v[52:53]
	v_lshl_add_u64 v[54:55], v[42:43], 0, v[54:55]
	global_load_dword v90, v[44:45], off nt
	global_load_dword v91, v[52:53], off nt
	global_load_dword v92, v[46:47], off nt
	global_load_dword v93, v[54:55], off nt
	v_lshl_add_u64 v[44:45], v[42:43], 0, v[48:49]
	v_lshlrev_b64 v[46:47], 12, v[8:9]
	v_lshl_add_u64 v[56:57], v[42:43], 0, v[56:57]
	v_lshl_add_u64 v[58:59], v[42:43], 0, v[58:59]
	v_lshl_add_u64 v[46:47], v[42:43], 0, v[46:47]
	global_load_dword v8, v[44:45], off nt
	global_load_dword v94, v[56:57], off nt
	global_load_dword v95, v[46:47], off nt
	global_load_dword v96, v[58:59], off nt
	s_add_i32 s29, s29, 16
	s_add_i32 s20, s20, 16
	s_add_i32 s48, s48, -16
	v_mad_u64_u32 v[44:45], s[50:51], v67, s47, v[10:11]
	s_cmp_lg_u32 s48, 0
	v_mad_u64_u32 v[46:47], s[50:51], v66, s47, v[10:11]
	v_mad_u64_u32 v[48:49], s[50:51], v69, s47, v[10:11]
	v_mad_u64_u32 v[50:51], s[50:51], v68, s47, v[10:11]
	v_mad_u64_u32 v[52:53], s[50:51], v71, s47, v[10:11]
	v_mad_u64_u32 v[54:55], s[50:51], v70, s47, v[10:11]
	v_mad_u64_u32 v[56:57], s[50:51], v73, s47, v[10:11]
	v_mad_u64_u32 v[58:59], s[50:51], v72, s47, v[10:11]
	v_mad_u64_u32 v[60:61], s[50:51], v75, s47, v[10:11]
	v_mad_u64_u32 v[62:63], s[50:51], v74, s47, v[10:11]
	v_mad_u64_u32 v[64:65], s[50:51], v77, s47, v[10:11]
	v_mad_u64_u32 v[66:67], s[50:51], v76, s47, v[10:11]
	v_mad_u64_u32 v[68:69], s[50:51], v79, s47, v[10:11]
	v_mad_u64_u32 v[70:71], s[50:51], v78, s47, v[10:11]
	v_mad_u64_u32 v[72:73], s[50:51], v81, s47, v[10:11]
	v_mad_u64_u32 v[74:75], s[50:51], v80, s47, v[10:11]
	s_waitcnt vmcnt(15)
	ds_write_b32 v44, v82
	s_waitcnt vmcnt(14)
	ds_write_b32 v46, v83
	s_waitcnt vmcnt(13)
	ds_write_b32 v48, v84
	s_waitcnt vmcnt(12)
	ds_write_b32 v50, v85
	s_waitcnt vmcnt(11)
	ds_write_b32 v52, v86
	s_waitcnt vmcnt(10)
	ds_write_b32 v54, v87
	s_waitcnt vmcnt(9)
	ds_write_b32 v56, v88
	s_waitcnt vmcnt(8)
	ds_write_b32 v58, v89
	s_waitcnt vmcnt(7)
	ds_write_b32 v60, v90
	s_waitcnt vmcnt(6)
	ds_write_b32 v62, v91
	s_waitcnt vmcnt(5)
	ds_write_b32 v64, v92
	s_waitcnt vmcnt(4)
	ds_write_b32 v66, v93
	s_waitcnt vmcnt(3)
	ds_write_b32 v68, v8
	s_waitcnt vmcnt(2)
	ds_write_b32 v70, v94
	s_waitcnt vmcnt(1)
	ds_write_b32 v72, v95
	s_waitcnt vmcnt(0)
	ds_write_b32 v74, v96
	s_cbranch_scc1 .LBB0_42
	s_lshl_b64 s[20:21], s[26:27], 23
	s_waitcnt lgkmcnt(0)
	s_add_u32 s20, s31, s20
	s_addc_u32 s21, s44, s21
	s_lshl_b32 s17, s17, 1
	ds_read2_b32 v[46:47], v5 offset0:33 offset1:41
	ds_read2_b32 v[48:49], v5 offset1:8
	ds_read2_b32 v[50:51], v5 offset0:66 offset1:74
	ds_read2_b32 v[52:53], v5 offset0:99 offset1:107
	ds_read2_b32 v[54:55], v5 offset0:132 offset1:140
	ds_read2_b32 v[56:57], v5 offset0:165 offset1:173
	ds_read2_b32 v[58:59], v5 offset0:198 offset1:206
	ds_read2_b32 v[60:61], v5 offset0:231 offset1:239
	s_add_u32 s20, s20, s17
	s_addc_u32 s21, s21, 0
	v_lshlrev_b32_e32 v8, 1, v12
	v_lshl_add_u64 v[62:63], s[20:21], 0, v[8:9]
	v_or_b32_e32 v8, s16, v3
	v_lshlrev_b32_e32 v8, 13, v8
	s_waitcnt lgkmcnt(6)
	v_cvt_pk_bf16_f32 v42, v48, v46
	s_waitcnt lgkmcnt(4)
	v_cvt_pk_bf16_f32 v43, v50, v52
	s_waitcnt lgkmcnt(2)
	v_cvt_pk_bf16_f32 v44, v54, v56
	s_waitcnt lgkmcnt(0)
	v_cvt_pk_bf16_f32 v45, v58, v60
	v_lshl_add_u64 v[64:65], v[62:63], 0, v[8:9]
	global_store_dwordx4 v[64:65], v[42:45], off
	v_or_b32_e32 v8, s16, v7
	v_lshlrev_b32_e32 v8, 13, v8
	v_cvt_pk_bf16_f32 v42, v49, v47
	v_cvt_pk_bf16_f32 v43, v51, v53
	v_cvt_pk_bf16_f32 v44, v55, v57
	v_cvt_pk_bf16_f32 v45, v59, v61
	ds_read2_b32 v[48:49], v5 offset0:49 offset1:57
	ds_read2_b32 v[50:51], v5 offset0:16 offset1:24
	ds_read2_b32 v[52:53], v5 offset0:82 offset1:90
	ds_read2_b32 v[54:55], v5 offset0:115 offset1:123
	ds_read2_b32 v[56:57], v5 offset0:148 offset1:156
	ds_read2_b32 v[58:59], v5 offset0:181 offset1:189
	ds_read2_b32 v[60:61], v5 offset0:214 offset1:222
	ds_read2_b32 v[64:65], v5 offset0:247 offset1:255
	v_lshl_add_u64 v[46:47], v[62:63], 0, v[8:9]
	v_or_b32_e32 v8, s16, v11
	v_lshlrev_b32_e32 v8, 13, v8
	global_store_dwordx4 v[46:47], v[42:45], off
	v_lshl_add_u64 v[46:47], v[62:63], 0, v[8:9]
	v_or_b32_e32 v8, s16, v13
	s_waitcnt lgkmcnt(6)
	v_cvt_pk_bf16_f32 v42, v50, v48
	s_waitcnt lgkmcnt(4)
	v_cvt_pk_bf16_f32 v43, v52, v54
	s_waitcnt lgkmcnt(2)
	v_cvt_pk_bf16_f32 v44, v56, v58
	s_waitcnt lgkmcnt(0)
	v_cvt_pk_bf16_f32 v45, v60, v64
	v_lshlrev_b32_e32 v8, 13, v8
	global_store_dwordx4 v[46:47], v[42:45], off
	v_lshl_add_u64 v[46:47], v[62:63], 0, v[8:9]
	s_nop 0
	v_cvt_pk_bf16_f32 v42, v51, v49
	v_cvt_pk_bf16_f32 v43, v53, v55
	v_cvt_pk_bf16_f32 v44, v57, v59
	v_cvt_pk_bf16_f32 v45, v61, v65
	global_store_dwordx4 v[46:47], v[42:45], off
	s_waitcnt lgkmcnt(0)

.LBB0_47:
	s_lshl_b32 s49, s20, 1
	s_lshl_b32 s50, s29, 1
	v_or_b32_e32 v67, s50, v4
	s_add_i32 s51, s49, 4
	s_add_i32 s52, s50, 4
	s_add_i32 s54, s50, 8
	v_add_u32_e32 v8, s17, v67
	v_or_b32_e32 v68, s51, v1
	v_or_b32_e32 v69, s52, v4
	v_mov_b32_e32 v47, v9
	v_or_b32_e32 v66, s49, v1
	s_add_i32 s56, s50, 12
	v_or_b32_e32 v71, s54, v4
	v_lshlrev_b64 v[60:61], 14, v[8:9]
	v_add_u32_e32 v46, s21, v68
	v_add_u32_e32 v8, s17, v69
	v_mov_b32_e32 v45, v9
	s_add_i32 s53, s49, 8
	s_add_i32 s55, s49, 12
	s_add_i32 s58, s50, 16
	v_add_u32_e32 v44, s21, v66
	v_or_b32_e32 v73, s56, v4
	v_lshlrev_b64 v[46:47], 14, v[46:47]
	v_lshlrev_b64 v[62:63], 14, v[8:9]
	v_add_u32_e32 v8, s17, v71
	s_add_i32 s60, s50, 20
	v_or_b32_e32 v70, s53, v1
	v_or_b32_e32 v72, s55, v1
	v_or_b32_e32 v75, s58, v4
	v_lshlrev_b64 v[44:45], 14, v[44:45]
	v_lshl_add_u64 v[60:61], v[42:43], 0, v[60:61]
	v_lshl_add_u64 v[46:47], v[42:43], 0, v[46:47]
	v_lshlrev_b64 v[64:65], 14, v[8:9]
	v_add_u32_e32 v8, s17, v73
	v_mov_b32_e32 v49, v9
	v_mov_b32_e32 v51, v9
	s_add_i32 s57, s49, 16
	s_add_i32 s59, s49, 20
	s_add_i32 s62, s50, 24
	v_or_b32_e32 v77, s60, v4
	v_add_u32_e32 v48, s21, v70
	v_add_u32_e32 v50, s21, v72
	v_lshl_add_u64 v[44:45], v[42:43], 0, v[44:45]
	v_lshl_add_u64 v[62:63], v[42:43], 0, v[62:63]
	global_load_dword v82, v[60:61], off nt
	global_load_dword v83, v[44:45], off nt
	global_load_dword v84, v[62:63], off nt
	global_load_dword v85, v[46:47], off nt
	v_lshlrev_b64 v[46:47], 14, v[8:9]
	v_add_u32_e32 v8, s17, v75
	s_add_i32 s61, s49, 24
	s_add_i32 s49, s49, 28
	s_add_i32 s50, s50, 28
	v_or_b32_e32 v74, s57, v1
	v_or_b32_e32 v76, s59, v1
	v_or_b32_e32 v79, s62, v4
	v_lshlrev_b64 v[48:49], 14, v[48:49]
	v_lshlrev_b64 v[50:51], 14, v[50:51]
	v_lshl_add_u64 v[44:45], v[42:43], 0, v[64:65]
	v_lshl_add_u64 v[46:47], v[42:43], 0, v[46:47]
	v_lshlrev_b64 v[60:61], 14, v[8:9]
	v_add_u32_e32 v8, s17, v77
	v_mov_b32_e32 v53, v9
	v_mov_b32_e32 v55, v9
	v_or_b32_e32 v78, s61, v1
	v_or_b32_e32 v80, s49, v1
	v_or_b32_e32 v81, s50, v4
	v_add_u32_e32 v52, s21, v74
	v_add_u32_e32 v54, s21, v76
	v_lshl_add_u64 v[48:49], v[42:43], 0, v[48:49]
	v_lshl_add_u64 v[50:51], v[42:43], 0, v[50:51]
	global_load_dword v86, v[44:45], off nt
	global_load_dword v87, v[48:49], off nt
	global_load_dword v88, v[46:47], off nt
	global_load_dword v89, v[50:51], off nt
	v_lshlrev_b64 v[46:47], 14, v[8:9]
	v_add_u32_e32 v8, s17, v79
	v_mov_b32_e32 v57, v9
	v_mov_b32_e32 v59, v9
	v_add_u32_e32 v56, s21, v78
	v_add_u32_e32 v58, s21, v80
	v_lshlrev_b64 v[52:53], 14, v[52:53]
	v_lshlrev_b64 v[54:55], 14, v[54:55]
	v_lshl_add_u64 v[44:45], v[42:43], 0, v[60:61]
	v_lshl_add_u64 v[46:47], v[42:43], 0, v[46:47]
	v_lshlrev_b64 v[48:49], 14, v[8:9]
	v_add_u32_e32 v8, s17, v81
	v_lshlrev_b64 v[56:57], 14, v[56:57]
	v_lshlrev_b64 v[58:59], 14, v[58:59]
	v_lshl_add_u64 v[52:53], v[42:43], 0, v[52:53]
	v_lshl_add_u64 v[54:55], v[42:43], 0, v[54:55]
	global_load_dword v90, v[44:45], off nt
	global_load_dword v91, v[52:53], off nt
	global_load_dword v92, v[46:47], off nt
	global_load_dword v93, v[54:55], off nt
	v_lshl_add_u64 v[44:45], v[42:43], 0, v[48:49]
	v_lshlrev_b64 v[46:47], 14, v[8:9]
	v_lshl_add_u64 v[56:57], v[42:43], 0, v[56:57]
	v_lshl_add_u64 v[58:59], v[42:43], 0, v[58:59]
	v_lshl_add_u64 v[46:47], v[42:43], 0, v[46:47]
	global_load_dword v8, v[44:45], off nt
	global_load_dword v94, v[56:57], off nt
	global_load_dword v95, v[46:47], off nt
	global_load_dword v96, v[58:59], off nt
	s_add_i32 s29, s29, 16
	s_add_i32 s20, s20, 16
	s_add_i32 s48, s48, -16
	v_mad_u64_u32 v[44:45], s[50:51], v67, s47, v[10:11]
	s_cmp_lg_u32 s48, 0
	v_mad_u64_u32 v[46:47], s[50:51], v66, s47, v[10:11]
	v_mad_u64_u32 v[48:49], s[50:51], v69, s47, v[10:11]
	v_mad_u64_u32 v[50:51], s[50:51], v68, s47, v[10:11]
	v_mad_u64_u32 v[52:53], s[50:51], v71, s47, v[10:11]
	v_mad_u64_u32 v[54:55], s[50:51], v70, s47, v[10:11]
	v_mad_u64_u32 v[56:57], s[50:51], v73, s47, v[10:11]
	v_mad_u64_u32 v[58:59], s[50:51], v72, s47, v[10:11]
	v_mad_u64_u32 v[60:61], s[50:51], v75, s47, v[10:11]
	v_mad_u64_u32 v[62:63], s[50:51], v74, s47, v[10:11]
	v_mad_u64_u32 v[64:65], s[50:51], v77, s47, v[10:11]
	v_mad_u64_u32 v[66:67], s[50:51], v76, s47, v[10:11]
	v_mad_u64_u32 v[68:69], s[50:51], v79, s47, v[10:11]
	v_mad_u64_u32 v[70:71], s[50:51], v78, s47, v[10:11]
	v_mad_u64_u32 v[72:73], s[50:51], v81, s47, v[10:11]
	v_mad_u64_u32 v[74:75], s[50:51], v80, s47, v[10:11]
	s_waitcnt vmcnt(15)
	ds_write_b32 v44, v82
	s_waitcnt vmcnt(14)
	ds_write_b32 v46, v83
	s_waitcnt vmcnt(13)
	ds_write_b32 v48, v84
	s_waitcnt vmcnt(12)
	ds_write_b32 v50, v85
	s_waitcnt vmcnt(11)
	ds_write_b32 v52, v86
	s_waitcnt vmcnt(10)
	ds_write_b32 v54, v87
	s_waitcnt vmcnt(9)
	ds_write_b32 v56, v88
	s_waitcnt vmcnt(8)
	ds_write_b32 v58, v89
	s_waitcnt vmcnt(7)
	ds_write_b32 v60, v90
	s_waitcnt vmcnt(6)
	ds_write_b32 v62, v91
	s_waitcnt vmcnt(5)
	ds_write_b32 v64, v92
	s_waitcnt vmcnt(4)
	ds_write_b32 v66, v93
	s_waitcnt vmcnt(3)
	ds_write_b32 v68, v8
	s_waitcnt vmcnt(2)
	ds_write_b32 v70, v94
	s_waitcnt vmcnt(1)
	ds_write_b32 v72, v95
	s_waitcnt vmcnt(0)
	ds_write_b32 v74, v96
	s_cbranch_scc1 .LBB0_47
	s_lshl_b64 s[20:21], s[26:27], 23
	s_waitcnt lgkmcnt(0)
	s_add_u32 s20, s45, s20
	s_addc_u32 s21, s46, s21
	s_lshl_b32 s17, s17, 1
	ds_read2_b32 v[46:47], v5 offset0:33 offset1:41
	ds_read2_b32 v[48:49], v5 offset1:8
	ds_read2_b32 v[50:51], v5 offset0:66 offset1:74
	ds_read2_b32 v[52:53], v5 offset0:99 offset1:107
	ds_read2_b32 v[54:55], v5 offset0:132 offset1:140
	ds_read2_b32 v[56:57], v5 offset0:165 offset1:173
	ds_read2_b32 v[58:59], v5 offset0:198 offset1:206
	ds_read2_b32 v[60:61], v5 offset0:231 offset1:239
	s_add_u32 s20, s20, s17
	s_addc_u32 s21, s21, 0
	v_lshlrev_b32_e32 v8, 1, v12
	v_lshl_add_u64 v[62:63], s[20:21], 0, v[8:9]
	v_or_b32_e32 v8, s16, v3
	v_lshlrev_b32_e32 v8, 11, v8
	s_waitcnt lgkmcnt(6)
	v_cvt_pk_bf16_f32 v42, v48, v46
	s_waitcnt lgkmcnt(4)
	v_cvt_pk_bf16_f32 v43, v50, v52
	s_waitcnt lgkmcnt(2)
	v_cvt_pk_bf16_f32 v44, v54, v56
	s_waitcnt lgkmcnt(0)
	v_cvt_pk_bf16_f32 v45, v58, v60
	v_lshl_add_u64 v[64:65], v[62:63], 0, v[8:9]
	global_store_dwordx4 v[64:65], v[42:45], off
	v_or_b32_e32 v8, s16, v7
	v_lshlrev_b32_e32 v8, 11, v8
	v_cvt_pk_bf16_f32 v42, v49, v47
	v_cvt_pk_bf16_f32 v43, v51, v53
	v_cvt_pk_bf16_f32 v44, v55, v57
	v_cvt_pk_bf16_f32 v45, v59, v61
	ds_read2_b32 v[48:49], v5 offset0:49 offset1:57
	ds_read2_b32 v[50:51], v5 offset0:16 offset1:24
	ds_read2_b32 v[52:53], v5 offset0:82 offset1:90
	ds_read2_b32 v[54:55], v5 offset0:115 offset1:123
	ds_read2_b32 v[56:57], v5 offset0:148 offset1:156
	ds_read2_b32 v[58:59], v5 offset0:181 offset1:189
	ds_read2_b32 v[60:61], v5 offset0:214 offset1:222
	ds_read2_b32 v[64:65], v5 offset0:247 offset1:255
	v_lshl_add_u64 v[46:47], v[62:63], 0, v[8:9]
	v_or_b32_e32 v8, s16, v11
	v_lshlrev_b32_e32 v8, 11, v8
	global_store_dwordx4 v[46:47], v[42:45], off
	v_lshl_add_u64 v[46:47], v[62:63], 0, v[8:9]
	v_or_b32_e32 v8, s16, v13
	s_waitcnt lgkmcnt(6)
	v_cvt_pk_bf16_f32 v42, v50, v48
	s_waitcnt lgkmcnt(4)
	v_cvt_pk_bf16_f32 v43, v52, v54
	s_waitcnt lgkmcnt(2)
	v_cvt_pk_bf16_f32 v44, v56, v58
	s_waitcnt lgkmcnt(0)
	v_cvt_pk_bf16_f32 v45, v60, v64
	v_lshlrev_b32_e32 v8, 11, v8
	global_store_dwordx4 v[46:47], v[42:45], off
	v_lshl_add_u64 v[46:47], v[62:63], 0, v[8:9]
	s_nop 0
	v_cvt_pk_bf16_f32 v42, v51, v49
	v_cvt_pk_bf16_f32 v43, v53, v55
	v_cvt_pk_bf16_f32 v44, v57, v59
	v_cvt_pk_bf16_f32 v45, v61, v65
	global_store_dwordx4 v[46:47], v[42:45], off
	s_waitcnt lgkmcnt(0)

.LBB0_52:
	s_lshl_b32 s48, s20, 1
	s_lshl_b32 s49, s26, 1
	v_or_b32_e32 v67, s49, v4
	s_add_i32 s50, s48, 4
	s_add_i32 s51, s49, 4
	s_add_i32 s53, s49, 8
	v_add_u32_e32 v8, s17, v67
	v_or_b32_e32 v68, s50, v1
	v_or_b32_e32 v69, s51, v4
	v_mov_b32_e32 v47, v9
	v_or_b32_e32 v66, s48, v1
	s_add_i32 s55, s49, 12
	v_or_b32_e32 v71, s53, v4
	v_lshlrev_b64 v[60:61], 12, v[8:9]
	v_add_u32_e32 v46, s21, v68
	v_add_u32_e32 v8, s17, v69
	v_mov_b32_e32 v45, v9
	s_add_i32 s52, s48, 8
	s_add_i32 s54, s48, 12
	s_add_i32 s57, s49, 16
	v_add_u32_e32 v44, s21, v66
	v_or_b32_e32 v73, s55, v4
	v_lshlrev_b64 v[46:47], 12, v[46:47]
	v_lshlrev_b64 v[62:63], 12, v[8:9]
	v_add_u32_e32 v8, s17, v71
	s_add_i32 s59, s49, 20
	v_or_b32_e32 v70, s52, v1
	v_or_b32_e32 v72, s54, v1
	v_or_b32_e32 v75, s57, v4
	v_lshlrev_b64 v[44:45], 12, v[44:45]
	v_lshl_add_u64 v[60:61], v[42:43], 0, v[60:61]
	v_lshl_add_u64 v[46:47], v[42:43], 0, v[46:47]
	v_lshlrev_b64 v[64:65], 12, v[8:9]
	v_add_u32_e32 v8, s17, v73
	v_mov_b32_e32 v49, v9
	v_mov_b32_e32 v51, v9
	s_add_i32 s56, s48, 16
	s_add_i32 s58, s48, 20
	s_add_i32 s61, s49, 24
	v_or_b32_e32 v77, s59, v4
	v_add_u32_e32 v48, s21, v70
	v_add_u32_e32 v50, s21, v72
	v_lshl_add_u64 v[44:45], v[42:43], 0, v[44:45]
	v_lshl_add_u64 v[62:63], v[42:43], 0, v[62:63]
	global_load_dword v82, v[60:61], off nt
	global_load_dword v83, v[44:45], off nt
	global_load_dword v84, v[62:63], off nt
	global_load_dword v85, v[46:47], off nt
	v_lshlrev_b64 v[46:47], 12, v[8:9]
	v_add_u32_e32 v8, s17, v75
	s_add_i32 s60, s48, 24
	s_add_i32 s48, s48, 28
	s_add_i32 s49, s49, 28
	v_or_b32_e32 v74, s56, v1
	v_or_b32_e32 v76, s58, v1
	v_or_b32_e32 v79, s61, v4
	v_lshlrev_b64 v[48:49], 12, v[48:49]
	v_lshlrev_b64 v[50:51], 12, v[50:51]
	v_lshl_add_u64 v[44:45], v[42:43], 0, v[64:65]
	v_lshl_add_u64 v[46:47], v[42:43], 0, v[46:47]
	v_lshlrev_b64 v[60:61], 12, v[8:9]
	v_add_u32_e32 v8, s17, v77
	v_mov_b32_e32 v53, v9
	v_mov_b32_e32 v55, v9
	v_or_b32_e32 v78, s60, v1
	v_or_b32_e32 v80, s48, v1
	v_or_b32_e32 v81, s49, v4
	v_add_u32_e32 v52, s21, v74
	v_add_u32_e32 v54, s21, v76
	v_lshl_add_u64 v[48:49], v[42:43], 0, v[48:49]
	v_lshl_add_u64 v[50:51], v[42:43], 0, v[50:51]
	global_load_dword v86, v[44:45], off nt
	global_load_dword v87, v[48:49], off nt
	global_load_dword v88, v[46:47], off nt
	global_load_dword v89, v[50:51], off nt
	v_lshlrev_b64 v[46:47], 12, v[8:9]
	v_add_u32_e32 v8, s17, v79
	v_mov_b32_e32 v57, v9
	v_mov_b32_e32 v59, v9
	v_add_u32_e32 v56, s21, v78
	v_add_u32_e32 v58, s21, v80
	v_lshlrev_b64 v[52:53], 12, v[52:53]
	v_lshlrev_b64 v[54:55], 12, v[54:55]
	v_lshl_add_u64 v[44:45], v[42:43], 0, v[60:61]
	v_lshl_add_u64 v[46:47], v[42:43], 0, v[46:47]
	v_lshlrev_b64 v[48:49], 12, v[8:9]
	v_add_u32_e32 v8, s17, v81
	v_lshlrev_b64 v[56:57], 12, v[56:57]
	v_lshlrev_b64 v[58:59], 12, v[58:59]
	v_lshl_add_u64 v[52:53], v[42:43], 0, v[52:53]
	v_lshl_add_u64 v[54:55], v[42:43], 0, v[54:55]
	global_load_dword v90, v[44:45], off nt
	global_load_dword v91, v[52:53], off nt
	global_load_dword v92, v[46:47], off nt
	global_load_dword v93, v[54:55], off nt
	v_lshl_add_u64 v[44:45], v[42:43], 0, v[48:49]
	v_lshlrev_b64 v[46:47], 12, v[8:9]
	v_lshl_add_u64 v[56:57], v[42:43], 0, v[56:57]
	v_lshl_add_u64 v[58:59], v[42:43], 0, v[58:59]
	v_lshl_add_u64 v[46:47], v[42:43], 0, v[46:47]
	global_load_dword v8, v[44:45], off nt
	global_load_dword v94, v[56:57], off nt
	global_load_dword v95, v[46:47], off nt
	global_load_dword v96, v[58:59], off nt
	s_add_i32 s26, s26, 16
	s_add_i32 s20, s20, 16
	s_add_i32 s29, s29, -16
	v_mad_u64_u32 v[44:45], s[48:49], v67, s47, v[10:11]
	s_cmp_lg_u32 s29, 0
	v_mad_u64_u32 v[46:47], s[48:49], v66, s47, v[10:11]
	v_mad_u64_u32 v[48:49], s[48:49], v69, s47, v[10:11]
	v_mad_u64_u32 v[50:51], s[48:49], v68, s47, v[10:11]
	v_mad_u64_u32 v[52:53], s[48:49], v71, s47, v[10:11]
	v_mad_u64_u32 v[54:55], s[48:49], v70, s47, v[10:11]
	v_mad_u64_u32 v[56:57], s[48:49], v73, s47, v[10:11]
	v_mad_u64_u32 v[58:59], s[48:49], v72, s47, v[10:11]
	v_mad_u64_u32 v[60:61], s[48:49], v75, s47, v[10:11]
	v_mad_u64_u32 v[62:63], s[48:49], v74, s47, v[10:11]
	v_mad_u64_u32 v[64:65], s[48:49], v77, s47, v[10:11]
	v_mad_u64_u32 v[66:67], s[48:49], v76, s47, v[10:11]
	v_mad_u64_u32 v[68:69], s[48:49], v79, s47, v[10:11]
	v_mad_u64_u32 v[70:71], s[48:49], v78, s47, v[10:11]
	v_mad_u64_u32 v[72:73], s[48:49], v81, s47, v[10:11]
	v_mad_u64_u32 v[74:75], s[48:49], v80, s47, v[10:11]
	s_waitcnt vmcnt(15)
	ds_write_b32 v44, v82
	s_waitcnt vmcnt(14)
	ds_write_b32 v46, v83
	s_waitcnt vmcnt(13)
	ds_write_b32 v48, v84
	s_waitcnt vmcnt(12)
	ds_write_b32 v50, v85
	s_waitcnt vmcnt(11)
	ds_write_b32 v52, v86
	s_waitcnt vmcnt(10)
	ds_write_b32 v54, v87
	s_waitcnt vmcnt(9)
	ds_write_b32 v56, v88
	s_waitcnt vmcnt(8)
	ds_write_b32 v58, v89
	s_waitcnt vmcnt(7)
	ds_write_b32 v60, v90
	s_waitcnt vmcnt(6)
	ds_write_b32 v62, v91
	s_waitcnt vmcnt(5)
	ds_write_b32 v64, v92
	s_waitcnt vmcnt(4)
	ds_write_b32 v66, v93
	s_waitcnt vmcnt(3)
	ds_write_b32 v68, v8
	s_waitcnt vmcnt(2)
	ds_write_b32 v70, v94
	s_waitcnt vmcnt(1)
	ds_write_b32 v72, v95
	s_waitcnt vmcnt(0)
	ds_write_b32 v74, v96
	s_cbranch_scc1 .LBB0_52
	s_waitcnt lgkmcnt(0)
	ds_read2_b32 v[46:47], v5 offset0:33 offset1:41
	ds_read2_b32 v[48:49], v5 offset1:8
	ds_read2_b32 v[50:51], v5 offset0:66 offset1:74
	ds_read2_b32 v[52:53], v5 offset0:99 offset1:107
	ds_read2_b32 v[54:55], v5 offset0:132 offset1:140
	ds_read2_b32 v[56:57], v5 offset0:165 offset1:173
	ds_read2_b32 v[58:59], v5 offset0:198 offset1:206
	ds_read2_b32 v[60:61], v5 offset0:231 offset1:239
	s_lshl_b32 s26, s17, 1
	v_or_b32_e32 v8, s16, v3
	v_lshl_add_u64 v[62:63], v[18:19], 0, s[26:27]
	v_lshlrev_b32_e32 v8, 11, v8
	s_waitcnt lgkmcnt(6)
	v_cvt_pk_bf16_f32 v42, v48, v46
	s_waitcnt lgkmcnt(4)
	v_cvt_pk_bf16_f32 v43, v50, v52
	s_waitcnt lgkmcnt(2)
	v_cvt_pk_bf16_f32 v44, v54, v56
	s_waitcnt lgkmcnt(0)
	v_cvt_pk_bf16_f32 v45, v58, v60
	v_lshl_add_u64 v[64:65], v[62:63], 0, v[8:9]
	global_store_dwordx4 v[64:65], v[42:45], off
	v_or_b32_e32 v8, s16, v7
	v_lshlrev_b32_e32 v8, 11, v8
	v_cvt_pk_bf16_f32 v42, v49, v47
	v_cvt_pk_bf16_f32 v43, v51, v53
	v_cvt_pk_bf16_f32 v44, v55, v57
	v_cvt_pk_bf16_f32 v45, v59, v61
	ds_read2_b32 v[48:49], v5 offset0:49 offset1:57
	ds_read2_b32 v[50:51], v5 offset0:16 offset1:24
	ds_read2_b32 v[52:53], v5 offset0:82 offset1:90
	ds_read2_b32 v[54:55], v5 offset0:115 offset1:123
	ds_read2_b32 v[56:57], v5 offset0:148 offset1:156
	ds_read2_b32 v[58:59], v5 offset0:181 offset1:189
	ds_read2_b32 v[60:61], v5 offset0:214 offset1:222
	ds_read2_b32 v[64:65], v5 offset0:247 offset1:255
	v_lshl_add_u64 v[46:47], v[62:63], 0, v[8:9]
	v_or_b32_e32 v8, s16, v11
	v_lshlrev_b32_e32 v8, 11, v8
	global_store_dwordx4 v[46:47], v[42:45], off
	v_lshl_add_u64 v[46:47], v[62:63], 0, v[8:9]
	v_or_b32_e32 v8, s16, v13
	s_waitcnt lgkmcnt(6)
	v_cvt_pk_bf16_f32 v42, v50, v48
	s_waitcnt lgkmcnt(4)
	v_cvt_pk_bf16_f32 v43, v52, v54
	s_waitcnt lgkmcnt(2)
	v_cvt_pk_bf16_f32 v44, v56, v58
	s_waitcnt lgkmcnt(0)
	v_cvt_pk_bf16_f32 v45, v60, v64
	v_lshlrev_b32_e32 v8, 11, v8
	global_store_dwordx4 v[46:47], v[42:45], off
	v_lshl_add_u64 v[46:47], v[62:63], 0, v[8:9]
	s_nop 0
	v_cvt_pk_bf16_f32 v42, v51, v49
	v_cvt_pk_bf16_f32 v43, v53, v55
	v_cvt_pk_bf16_f32 v44, v57, v59
	v_cvt_pk_bf16_f32 v45, v61, v65
	global_store_dwordx4 v[46:47], v[42:45], off
	s_waitcnt lgkmcnt(0)

.LBB0_57:
	s_lshl_b32 s48, s20, 1
	s_lshl_b32 s49, s26, 1
	v_or_b32_e32 v67, s49, v4
	s_add_i32 s50, s48, 4
	s_add_i32 s51, s49, 4
	s_add_i32 s53, s49, 8
	v_add_u32_e32 v8, s17, v67
	v_or_b32_e32 v68, s50, v1
	v_or_b32_e32 v69, s51, v4
	v_mov_b32_e32 v47, v9
	v_or_b32_e32 v66, s48, v1
	s_add_i32 s55, s49, 12
	v_or_b32_e32 v71, s53, v4
	v_lshlrev_b64 v[60:61], 12, v[8:9]
	v_add_u32_e32 v46, s21, v68
	v_add_u32_e32 v8, s17, v69
	v_mov_b32_e32 v45, v9
	s_add_i32 s52, s48, 8
	s_add_i32 s54, s48, 12
	s_add_i32 s57, s49, 16
	v_add_u32_e32 v44, s21, v66
	v_or_b32_e32 v73, s55, v4
	v_lshlrev_b64 v[46:47], 12, v[46:47]
	v_lshlrev_b64 v[62:63], 12, v[8:9]
	v_add_u32_e32 v8, s17, v71
	s_add_i32 s59, s49, 20
	v_or_b32_e32 v70, s52, v1
	v_or_b32_e32 v72, s54, v1
	v_or_b32_e32 v75, s57, v4
	v_lshlrev_b64 v[44:45], 12, v[44:45]
	v_lshl_add_u64 v[60:61], v[42:43], 0, v[60:61]
	v_lshl_add_u64 v[46:47], v[42:43], 0, v[46:47]
	v_lshlrev_b64 v[64:65], 12, v[8:9]
	v_add_u32_e32 v8, s17, v73
	v_mov_b32_e32 v49, v9
	v_mov_b32_e32 v51, v9
	s_add_i32 s56, s48, 16
	s_add_i32 s58, s48, 20
	s_add_i32 s61, s49, 24
	v_or_b32_e32 v77, s59, v4
	v_add_u32_e32 v48, s21, v70
	v_add_u32_e32 v50, s21, v72
	v_lshl_add_u64 v[44:45], v[42:43], 0, v[44:45]
	v_lshl_add_u64 v[62:63], v[42:43], 0, v[62:63]
	global_load_dword v82, v[60:61], off nt
	global_load_dword v83, v[44:45], off nt
	global_load_dword v84, v[62:63], off nt
	global_load_dword v85, v[46:47], off nt
	v_lshlrev_b64 v[46:47], 12, v[8:9]
	v_add_u32_e32 v8, s17, v75
	s_add_i32 s60, s48, 24
	s_add_i32 s48, s48, 28
	s_add_i32 s49, s49, 28
	v_or_b32_e32 v74, s56, v1
	v_or_b32_e32 v76, s58, v1
	v_or_b32_e32 v79, s61, v4
	v_lshlrev_b64 v[48:49], 12, v[48:49]
	v_lshlrev_b64 v[50:51], 12, v[50:51]
	v_lshl_add_u64 v[44:45], v[42:43], 0, v[64:65]
	v_lshl_add_u64 v[46:47], v[42:43], 0, v[46:47]
	v_lshlrev_b64 v[60:61], 12, v[8:9]
	v_add_u32_e32 v8, s17, v77
	v_mov_b32_e32 v53, v9
	v_mov_b32_e32 v55, v9
	v_or_b32_e32 v78, s60, v1
	v_or_b32_e32 v80, s48, v1
	v_or_b32_e32 v81, s49, v4
	v_add_u32_e32 v52, s21, v74
	v_add_u32_e32 v54, s21, v76
	v_lshl_add_u64 v[48:49], v[42:43], 0, v[48:49]
	v_lshl_add_u64 v[50:51], v[42:43], 0, v[50:51]
	global_load_dword v86, v[44:45], off nt
	global_load_dword v87, v[48:49], off nt
	global_load_dword v88, v[46:47], off nt
	global_load_dword v89, v[50:51], off nt
	v_lshlrev_b64 v[46:47], 12, v[8:9]
	v_add_u32_e32 v8, s17, v79
	v_mov_b32_e32 v57, v9
	v_mov_b32_e32 v59, v9
	v_add_u32_e32 v56, s21, v78
	v_add_u32_e32 v58, s21, v80
	v_lshlrev_b64 v[52:53], 12, v[52:53]
	v_lshlrev_b64 v[54:55], 12, v[54:55]
	v_lshl_add_u64 v[44:45], v[42:43], 0, v[60:61]
	v_lshl_add_u64 v[46:47], v[42:43], 0, v[46:47]
	v_lshlrev_b64 v[48:49], 12, v[8:9]
	v_add_u32_e32 v8, s17, v81
	v_lshlrev_b64 v[56:57], 12, v[56:57]
	v_lshlrev_b64 v[58:59], 12, v[58:59]
	v_lshl_add_u64 v[52:53], v[42:43], 0, v[52:53]
	v_lshl_add_u64 v[54:55], v[42:43], 0, v[54:55]
	global_load_dword v90, v[44:45], off nt
	global_load_dword v91, v[52:53], off nt
	global_load_dword v92, v[46:47], off nt
	global_load_dword v93, v[54:55], off nt
	v_lshl_add_u64 v[44:45], v[42:43], 0, v[48:49]
	v_lshlrev_b64 v[46:47], 12, v[8:9]
	v_lshl_add_u64 v[56:57], v[42:43], 0, v[56:57]
	v_lshl_add_u64 v[58:59], v[42:43], 0, v[58:59]
	v_lshl_add_u64 v[46:47], v[42:43], 0, v[46:47]
	global_load_dword v8, v[44:45], off nt
	global_load_dword v94, v[56:57], off nt
	global_load_dword v95, v[46:47], off nt
	global_load_dword v96, v[58:59], off nt
	s_add_i32 s26, s26, 16
	s_add_i32 s20, s20, 16
	s_add_i32 s29, s29, -16
	v_mad_u64_u32 v[44:45], s[48:49], v67, s47, v[10:11]
	s_cmp_lg_u32 s29, 0
	v_mad_u64_u32 v[46:47], s[48:49], v66, s47, v[10:11]
	v_mad_u64_u32 v[48:49], s[48:49], v69, s47, v[10:11]
	v_mad_u64_u32 v[50:51], s[48:49], v68, s47, v[10:11]
	v_mad_u64_u32 v[52:53], s[48:49], v71, s47, v[10:11]
	v_mad_u64_u32 v[54:55], s[48:49], v70, s47, v[10:11]
	v_mad_u64_u32 v[56:57], s[48:49], v73, s47, v[10:11]
	v_mad_u64_u32 v[58:59], s[48:49], v72, s47, v[10:11]
	v_mad_u64_u32 v[60:61], s[48:49], v75, s47, v[10:11]
	v_mad_u64_u32 v[62:63], s[48:49], v74, s47, v[10:11]
	v_mad_u64_u32 v[64:65], s[48:49], v77, s47, v[10:11]
	v_mad_u64_u32 v[66:67], s[48:49], v76, s47, v[10:11]
	v_mad_u64_u32 v[68:69], s[48:49], v79, s47, v[10:11]
	v_mad_u64_u32 v[70:71], s[48:49], v78, s47, v[10:11]
	v_mad_u64_u32 v[72:73], s[48:49], v81, s47, v[10:11]
	v_mad_u64_u32 v[74:75], s[48:49], v80, s47, v[10:11]
	s_waitcnt vmcnt(15)
	ds_write_b32 v44, v82
	s_waitcnt vmcnt(14)
	ds_write_b32 v46, v83
	s_waitcnt vmcnt(13)
	ds_write_b32 v48, v84
	s_waitcnt vmcnt(12)
	ds_write_b32 v50, v85
	s_waitcnt vmcnt(11)
	ds_write_b32 v52, v86
	s_waitcnt vmcnt(10)
	ds_write_b32 v54, v87
	s_waitcnt vmcnt(9)
	ds_write_b32 v56, v88
	s_waitcnt vmcnt(8)
	ds_write_b32 v58, v89
	s_waitcnt vmcnt(7)
	ds_write_b32 v60, v90
	s_waitcnt vmcnt(6)
	ds_write_b32 v62, v91
	s_waitcnt vmcnt(5)
	ds_write_b32 v64, v92
	s_waitcnt vmcnt(4)
	ds_write_b32 v66, v93
	s_waitcnt vmcnt(3)
	ds_write_b32 v68, v8
	s_waitcnt vmcnt(2)
	ds_write_b32 v70, v94
	s_waitcnt vmcnt(1)
	ds_write_b32 v72, v95
	s_waitcnt vmcnt(0)
	ds_write_b32 v74, v96
	s_cbranch_scc1 .LBB0_57
	s_waitcnt lgkmcnt(0)
	ds_read2_b32 v[46:47], v5 offset0:33 offset1:41
	ds_read2_b32 v[48:49], v5 offset1:8
	ds_read2_b32 v[50:51], v5 offset0:66 offset1:74
	ds_read2_b32 v[52:53], v5 offset0:99 offset1:107
	ds_read2_b32 v[54:55], v5 offset0:132 offset1:140
	ds_read2_b32 v[56:57], v5 offset0:165 offset1:173
	ds_read2_b32 v[58:59], v5 offset0:198 offset1:206
	ds_read2_b32 v[60:61], v5 offset0:231 offset1:239
	s_lshl_b32 s26, s17, 1
	v_or_b32_e32 v8, s16, v3
	v_lshl_add_u64 v[62:63], v[20:21], 0, s[26:27]
	v_lshlrev_b32_e32 v8, 9, v8
	s_waitcnt lgkmcnt(6)
	v_cvt_pk_bf16_f32 v42, v48, v46
	s_waitcnt lgkmcnt(4)
	v_cvt_pk_bf16_f32 v43, v50, v52
	s_waitcnt lgkmcnt(2)
	v_cvt_pk_bf16_f32 v44, v54, v56
	s_waitcnt lgkmcnt(0)
	v_cvt_pk_bf16_f32 v45, v58, v60
	v_lshl_add_u64 v[64:65], v[62:63], 0, v[8:9]
	global_store_dwordx4 v[64:65], v[42:45], off
	v_or_b32_e32 v8, s16, v7
	v_lshlrev_b32_e32 v8, 9, v8
	v_cvt_pk_bf16_f32 v42, v49, v47
	v_cvt_pk_bf16_f32 v43, v51, v53
	v_cvt_pk_bf16_f32 v44, v55, v57
	v_cvt_pk_bf16_f32 v45, v59, v61
	ds_read2_b32 v[48:49], v5 offset0:49 offset1:57
	ds_read2_b32 v[50:51], v5 offset0:16 offset1:24
	ds_read2_b32 v[52:53], v5 offset0:82 offset1:90
	ds_read2_b32 v[54:55], v5 offset0:115 offset1:123
	ds_read2_b32 v[56:57], v5 offset0:148 offset1:156
	ds_read2_b32 v[58:59], v5 offset0:181 offset1:189
	ds_read2_b32 v[60:61], v5 offset0:214 offset1:222
	ds_read2_b32 v[64:65], v5 offset0:247 offset1:255
	v_lshl_add_u64 v[46:47], v[62:63], 0, v[8:9]
	v_or_b32_e32 v8, s16, v11
	v_lshlrev_b32_e32 v8, 9, v8
	global_store_dwordx4 v[46:47], v[42:45], off
	v_lshl_add_u64 v[46:47], v[62:63], 0, v[8:9]
	v_or_b32_e32 v8, s16, v13
	s_waitcnt lgkmcnt(6)
	v_cvt_pk_bf16_f32 v42, v50, v48
	s_waitcnt lgkmcnt(4)
	v_cvt_pk_bf16_f32 v43, v52, v54
	s_waitcnt lgkmcnt(2)
	v_cvt_pk_bf16_f32 v44, v56, v58
	s_waitcnt lgkmcnt(0)
	v_cvt_pk_bf16_f32 v45, v60, v64
	v_lshlrev_b32_e32 v8, 9, v8
	global_store_dwordx4 v[46:47], v[42:45], off
	v_lshl_add_u64 v[46:47], v[62:63], 0, v[8:9]
	s_nop 0
	v_cvt_pk_bf16_f32 v42, v51, v49
	v_cvt_pk_bf16_f32 v43, v53, v55
	v_cvt_pk_bf16_f32 v44, v57, v59
	v_cvt_pk_bf16_f32 v45, v61, v65
	global_store_dwordx4 v[46:47], v[42:45], off
	s_waitcnt lgkmcnt(0)

.LBB0_62:
	s_lshl_b32 s48, s20, 1
	s_lshl_b32 s49, s26, 1
	v_or_b32_e32 v67, s49, v4
	s_add_i32 s50, s48, 4
	s_add_i32 s51, s49, 4
	s_add_i32 s53, s49, 8
	v_add_u32_e32 v8, s17, v67
	v_or_b32_e32 v68, s50, v1
	v_or_b32_e32 v69, s51, v4
	v_mov_b32_e32 v47, v9
	v_or_b32_e32 v66, s48, v1
	s_add_i32 s55, s49, 12
	v_or_b32_e32 v71, s53, v4
	v_lshlrev_b64 v[60:61], 12, v[8:9]
	v_add_u32_e32 v46, s21, v68
	v_add_u32_e32 v8, s17, v69
	v_mov_b32_e32 v45, v9
	s_add_i32 s52, s48, 8
	s_add_i32 s54, s48, 12
	s_add_i32 s57, s49, 16
	v_add_u32_e32 v44, s21, v66
	v_or_b32_e32 v73, s55, v4
	v_lshlrev_b64 v[46:47], 12, v[46:47]
	v_lshlrev_b64 v[62:63], 12, v[8:9]
	v_add_u32_e32 v8, s17, v71
	s_add_i32 s59, s49, 20
	v_or_b32_e32 v70, s52, v1
	v_or_b32_e32 v72, s54, v1
	v_or_b32_e32 v75, s57, v4
	v_lshlrev_b64 v[44:45], 12, v[44:45]
	v_lshl_add_u64 v[60:61], v[42:43], 0, v[60:61]
	v_lshl_add_u64 v[46:47], v[42:43], 0, v[46:47]
	v_lshlrev_b64 v[64:65], 12, v[8:9]
	v_add_u32_e32 v8, s17, v73
	v_mov_b32_e32 v49, v9
	v_mov_b32_e32 v51, v9
	s_add_i32 s56, s48, 16
	s_add_i32 s58, s48, 20
	s_add_i32 s61, s49, 24
	v_or_b32_e32 v77, s59, v4
	v_add_u32_e32 v48, s21, v70
	v_add_u32_e32 v50, s21, v72
	v_lshl_add_u64 v[44:45], v[42:43], 0, v[44:45]
	v_lshl_add_u64 v[62:63], v[42:43], 0, v[62:63]
	global_load_dword v82, v[60:61], off nt
	global_load_dword v83, v[44:45], off nt
	global_load_dword v84, v[62:63], off nt
	global_load_dword v85, v[46:47], off nt
	v_lshlrev_b64 v[46:47], 12, v[8:9]
	v_add_u32_e32 v8, s17, v75
	s_add_i32 s60, s48, 24
	s_add_i32 s48, s48, 28
	s_add_i32 s49, s49, 28
	v_or_b32_e32 v74, s56, v1
	v_or_b32_e32 v76, s58, v1
	v_or_b32_e32 v79, s61, v4
	v_lshlrev_b64 v[48:49], 12, v[48:49]
	v_lshlrev_b64 v[50:51], 12, v[50:51]
	v_lshl_add_u64 v[44:45], v[42:43], 0, v[64:65]
	v_lshl_add_u64 v[46:47], v[42:43], 0, v[46:47]
	v_lshlrev_b64 v[60:61], 12, v[8:9]
	v_add_u32_e32 v8, s17, v77
	v_mov_b32_e32 v53, v9
	v_mov_b32_e32 v55, v9
	v_or_b32_e32 v78, s60, v1
	v_or_b32_e32 v80, s48, v1
	v_or_b32_e32 v81, s49, v4
	v_add_u32_e32 v52, s21, v74
	v_add_u32_e32 v54, s21, v76
	v_lshl_add_u64 v[48:49], v[42:43], 0, v[48:49]
	v_lshl_add_u64 v[50:51], v[42:43], 0, v[50:51]
	global_load_dword v86, v[44:45], off nt
	global_load_dword v87, v[48:49], off nt
	global_load_dword v88, v[46:47], off nt
	global_load_dword v89, v[50:51], off nt
	v_lshlrev_b64 v[46:47], 12, v[8:9]
	v_add_u32_e32 v8, s17, v79
	v_mov_b32_e32 v57, v9
	v_mov_b32_e32 v59, v9
	v_add_u32_e32 v56, s21, v78
	v_add_u32_e32 v58, s21, v80
	v_lshlrev_b64 v[52:53], 12, v[52:53]
	v_lshlrev_b64 v[54:55], 12, v[54:55]
	v_lshl_add_u64 v[44:45], v[42:43], 0, v[60:61]
	v_lshl_add_u64 v[46:47], v[42:43], 0, v[46:47]
	v_lshlrev_b64 v[48:49], 12, v[8:9]
	v_add_u32_e32 v8, s17, v81
	v_lshlrev_b64 v[56:57], 12, v[56:57]
	v_lshlrev_b64 v[58:59], 12, v[58:59]
	v_lshl_add_u64 v[52:53], v[42:43], 0, v[52:53]
	v_lshl_add_u64 v[54:55], v[42:43], 0, v[54:55]
	global_load_dword v90, v[44:45], off nt
	global_load_dword v91, v[52:53], off nt
	global_load_dword v92, v[46:47], off nt
	global_load_dword v93, v[54:55], off nt
	v_lshl_add_u64 v[44:45], v[42:43], 0, v[48:49]
	v_lshlrev_b64 v[46:47], 12, v[8:9]
	v_lshl_add_u64 v[56:57], v[42:43], 0, v[56:57]
	v_lshl_add_u64 v[58:59], v[42:43], 0, v[58:59]
	v_lshl_add_u64 v[46:47], v[42:43], 0, v[46:47]
	global_load_dword v8, v[44:45], off nt
	global_load_dword v94, v[56:57], off nt
	global_load_dword v95, v[46:47], off nt
	global_load_dword v96, v[58:59], off nt
	s_add_i32 s26, s26, 16
	s_add_i32 s20, s20, 16
	s_add_i32 s29, s29, -16
	v_mad_u64_u32 v[44:45], s[48:49], v67, s47, v[10:11]
	s_cmp_lg_u32 s29, 0
	v_mad_u64_u32 v[46:47], s[48:49], v66, s47, v[10:11]
	v_mad_u64_u32 v[48:49], s[48:49], v69, s47, v[10:11]
	v_mad_u64_u32 v[50:51], s[48:49], v68, s47, v[10:11]
	v_mad_u64_u32 v[52:53], s[48:49], v71, s47, v[10:11]
	v_mad_u64_u32 v[54:55], s[48:49], v70, s47, v[10:11]
	v_mad_u64_u32 v[56:57], s[48:49], v73, s47, v[10:11]
	v_mad_u64_u32 v[58:59], s[48:49], v72, s47, v[10:11]
	v_mad_u64_u32 v[60:61], s[48:49], v75, s47, v[10:11]
	v_mad_u64_u32 v[62:63], s[48:49], v74, s47, v[10:11]
	v_mad_u64_u32 v[64:65], s[48:49], v77, s47, v[10:11]
	v_mad_u64_u32 v[66:67], s[48:49], v76, s47, v[10:11]
	v_mad_u64_u32 v[68:69], s[48:49], v79, s47, v[10:11]
	v_mad_u64_u32 v[70:71], s[48:49], v78, s47, v[10:11]
	v_mad_u64_u32 v[72:73], s[48:49], v81, s47, v[10:11]
	v_mad_u64_u32 v[74:75], s[48:49], v80, s47, v[10:11]
	s_waitcnt vmcnt(15)
	ds_write_b32 v44, v82
	s_waitcnt vmcnt(14)
	ds_write_b32 v46, v83
	s_waitcnt vmcnt(13)
	ds_write_b32 v48, v84
	s_waitcnt vmcnt(12)
	ds_write_b32 v50, v85
	s_waitcnt vmcnt(11)
	ds_write_b32 v52, v86
	s_waitcnt vmcnt(10)
	ds_write_b32 v54, v87
	s_waitcnt vmcnt(9)
	ds_write_b32 v56, v88
	s_waitcnt vmcnt(8)
	ds_write_b32 v58, v89
	s_waitcnt vmcnt(7)
	ds_write_b32 v60, v90
	s_waitcnt vmcnt(6)
	ds_write_b32 v62, v91
	s_waitcnt vmcnt(5)
	ds_write_b32 v64, v92
	s_waitcnt vmcnt(4)
	ds_write_b32 v66, v93
	s_waitcnt vmcnt(3)
	ds_write_b32 v68, v8
	s_waitcnt vmcnt(2)
	ds_write_b32 v70, v94
	s_waitcnt vmcnt(1)
	ds_write_b32 v72, v95
	s_waitcnt vmcnt(0)
	ds_write_b32 v74, v96
	s_cbranch_scc1 .LBB0_62
	s_waitcnt lgkmcnt(0)
	ds_read2_b32 v[46:47], v5 offset0:33 offset1:41
	ds_read2_b32 v[48:49], v5 offset1:8
	ds_read2_b32 v[50:51], v5 offset0:66 offset1:74
	ds_read2_b32 v[52:53], v5 offset0:99 offset1:107
	ds_read2_b32 v[54:55], v5 offset0:132 offset1:140
	ds_read2_b32 v[56:57], v5 offset0:165 offset1:173
	ds_read2_b32 v[58:59], v5 offset0:198 offset1:206
	ds_read2_b32 v[60:61], v5 offset0:231 offset1:239
	s_lshl_b32 s26, s17, 1
	v_or_b32_e32 v8, s16, v3
	v_lshl_add_u64 v[62:63], v[22:23], 0, s[26:27]
	v_lshlrev_b32_e32 v8, 9, v8
	s_waitcnt lgkmcnt(6)
	v_cvt_pk_bf16_f32 v42, v48, v46
	s_waitcnt lgkmcnt(4)
	v_cvt_pk_bf16_f32 v43, v50, v52
	s_waitcnt lgkmcnt(2)
	v_cvt_pk_bf16_f32 v44, v54, v56
	s_waitcnt lgkmcnt(0)
	v_cvt_pk_bf16_f32 v45, v58, v60
	v_lshl_add_u64 v[64:65], v[62:63], 0, v[8:9]
	global_store_dwordx4 v[64:65], v[42:45], off
	v_or_b32_e32 v8, s16, v7
	v_lshlrev_b32_e32 v8, 9, v8
	v_cvt_pk_bf16_f32 v42, v49, v47
	v_cvt_pk_bf16_f32 v43, v51, v53
	v_cvt_pk_bf16_f32 v44, v55, v57
	v_cvt_pk_bf16_f32 v45, v59, v61
	ds_read2_b32 v[48:49], v5 offset0:49 offset1:57
	ds_read2_b32 v[50:51], v5 offset0:16 offset1:24
	ds_read2_b32 v[52:53], v5 offset0:82 offset1:90
	ds_read2_b32 v[54:55], v5 offset0:115 offset1:123
	ds_read2_b32 v[56:57], v5 offset0:148 offset1:156
	ds_read2_b32 v[58:59], v5 offset0:181 offset1:189
	ds_read2_b32 v[60:61], v5 offset0:214 offset1:222
	ds_read2_b32 v[64:65], v5 offset0:247 offset1:255
	v_lshl_add_u64 v[46:47], v[62:63], 0, v[8:9]
	v_or_b32_e32 v8, s16, v11
	v_lshlrev_b32_e32 v8, 9, v8
	global_store_dwordx4 v[46:47], v[42:45], off
	v_lshl_add_u64 v[46:47], v[62:63], 0, v[8:9]
	v_or_b32_e32 v8, s16, v13
	s_waitcnt lgkmcnt(6)
	v_cvt_pk_bf16_f32 v42, v50, v48
	s_waitcnt lgkmcnt(4)
	v_cvt_pk_bf16_f32 v43, v52, v54
	s_waitcnt lgkmcnt(2)
	v_cvt_pk_bf16_f32 v44, v56, v58
	s_waitcnt lgkmcnt(0)
	v_cvt_pk_bf16_f32 v45, v60, v64
	v_lshlrev_b32_e32 v8, 9, v8
	global_store_dwordx4 v[46:47], v[42:45], off
	v_lshl_add_u64 v[46:47], v[62:63], 0, v[8:9]
	s_nop 0
	v_cvt_pk_bf16_f32 v42, v51, v49
	v_cvt_pk_bf16_f32 v43, v53, v55
	v_cvt_pk_bf16_f32 v44, v57, v59
	v_cvt_pk_bf16_f32 v45, v61, v65
	global_store_dwordx4 v[46:47], v[42:45], off
	s_waitcnt lgkmcnt(0)

.LBB0_71:
	s_lshl_b32 s48, s21, 1
	s_lshl_b32 s49, s26, 1
	v_or_b32_e32 v8, s48, v1
	v_or_b32_e32 v76, s49, v4
	s_add_i32 s50, s48, 4
	s_add_i32 s51, s49, 4
	s_add_i32 s52, s48, 8
	s_add_i32 s53, s49, 8
	s_add_i32 s54, s48, 12
	s_add_i32 s55, s49, 12
	s_add_i32 s56, s48, 16
	s_add_i32 s57, s49, 16
	s_add_i32 s58, s48, 20
	s_add_i32 s59, s49, 20
	s_add_i32 s60, s48, 24
	s_add_i32 s61, s49, 24
	s_add_i32 s48, s48, 28
	s_add_i32 s49, s49, 28
	v_add_u32_e32 v44, s16, v76
	v_or_b32_e32 v77, s50, v1
	v_or_b32_e32 v78, s51, v4
	v_or_b32_e32 v79, s52, v1
	v_or_b32_e32 v80, s53, v4
	v_or_b32_e32 v81, s54, v1
	v_or_b32_e32 v82, s55, v4
	v_or_b32_e32 v83, s56, v1
	v_or_b32_e32 v84, s57, v4
	v_or_b32_e32 v85, s58, v1
	v_or_b32_e32 v86, s59, v4
	v_or_b32_e32 v87, s60, v1
	v_or_b32_e32 v88, s61, v4
	v_or_b32_e32 v89, s48, v1
	v_or_b32_e32 v90, s49, v4
	v_add_u32_e32 v46, s17, v8
	v_mad_u64_u32 v[44:45], s[48:49], v44, s23, v[42:43]
	v_add_u32_e32 v50, s17, v77
	v_add_u32_e32 v48, s16, v78
	v_add_u32_e32 v54, s17, v79
	v_add_u32_e32 v52, s16, v80
	v_add_u32_e32 v58, s17, v81
	v_add_u32_e32 v56, s16, v82
	v_add_u32_e32 v62, s17, v83
	v_add_u32_e32 v60, s16, v84
	v_add_u32_e32 v66, s17, v85
	v_add_u32_e32 v64, s16, v86
	v_add_u32_e32 v70, s17, v87
	v_add_u32_e32 v68, s16, v88
	v_add_u32_e32 v74, s17, v89
	v_add_u32_e32 v72, s16, v90
	v_mad_u64_u32 v[46:47], s[48:49], v46, s23, v[42:43]
	v_mad_u64_u32 v[48:49], s[48:49], v48, s23, v[42:43]
	v_mad_u64_u32 v[50:51], s[48:49], v50, s23, v[42:43]
	v_mad_u64_u32 v[52:53], s[48:49], v52, s23, v[42:43]
	v_mad_u64_u32 v[54:55], s[48:49], v54, s23, v[42:43]
	v_mad_u64_u32 v[56:57], s[48:49], v56, s23, v[42:43]
	v_mad_u64_u32 v[58:59], s[48:49], v58, s23, v[42:43]
	v_mad_u64_u32 v[60:61], s[48:49], v60, s23, v[42:43]
	v_mad_u64_u32 v[62:63], s[48:49], v62, s23, v[42:43]
	v_mad_u64_u32 v[64:65], s[48:49], v64, s23, v[42:43]
	v_mad_u64_u32 v[66:67], s[48:49], v66, s23, v[42:43]
	v_mad_u64_u32 v[68:69], s[48:49], v68, s23, v[42:43]
	v_mad_u64_u32 v[70:71], s[48:49], v70, s23, v[42:43]
	v_mad_u64_u32 v[72:73], s[48:49], v72, s23, v[42:43]
	v_mad_u64_u32 v[74:75], s[48:49], v74, s23, v[42:43]
	global_load_dword v91, v[44:45], off nt
	global_load_dword v92, v[46:47], off nt
	global_load_dword v93, v[48:49], off nt
	global_load_dword v94, v[50:51], off nt
	global_load_dword v95, v[52:53], off nt
	global_load_dword v96, v[54:55], off nt
	global_load_dword v97, v[56:57], off nt
	global_load_dword v98, v[58:59], off nt
	global_load_dword v99, v[60:61], off nt
	global_load_dword v100, v[62:63], off nt
	global_load_dword v101, v[64:65], off nt
	global_load_dword v102, v[66:67], off nt
	global_load_dword v103, v[68:69], off nt
	global_load_dword v104, v[70:71], off nt
	global_load_dword v105, v[72:73], off nt
	global_load_dword v106, v[74:75], off nt
	s_add_i32 s26, s26, 16
	s_add_i32 s21, s21, 16
	s_add_i32 s29, s29, -16
	v_mad_u64_u32 v[44:45], s[48:49], v76, s47, v[10:11]
	s_cmp_lg_u32 s29, 0
	v_mad_u64_u32 v[46:47], s[48:49], v8, s47, v[10:11]
	v_mad_u64_u32 v[48:49], s[48:49], v78, s47, v[10:11]
	v_mad_u64_u32 v[50:51], s[48:49], v77, s47, v[10:11]
	v_mad_u64_u32 v[52:53], s[48:49], v80, s47, v[10:11]
	v_mad_u64_u32 v[54:55], s[48:49], v79, s47, v[10:11]
	v_mad_u64_u32 v[56:57], s[48:49], v82, s47, v[10:11]
	v_mad_u64_u32 v[58:59], s[48:49], v81, s47, v[10:11]
	v_mad_u64_u32 v[60:61], s[48:49], v84, s47, v[10:11]
	v_mad_u64_u32 v[62:63], s[48:49], v83, s47, v[10:11]
	v_mad_u64_u32 v[64:65], s[48:49], v86, s47, v[10:11]
	v_mad_u64_u32 v[66:67], s[48:49], v85, s47, v[10:11]
	v_mad_u64_u32 v[68:69], s[48:49], v88, s47, v[10:11]
	v_mad_u64_u32 v[70:71], s[48:49], v87, s47, v[10:11]
	v_mad_u64_u32 v[72:73], s[48:49], v90, s47, v[10:11]
	v_mad_u64_u32 v[74:75], s[48:49], v89, s47, v[10:11]
	s_waitcnt vmcnt(15)
	ds_write_b32 v44, v91
	s_waitcnt vmcnt(14)
	ds_write_b32 v46, v92
	s_waitcnt vmcnt(13)
	ds_write_b32 v48, v93
	s_waitcnt vmcnt(12)
	ds_write_b32 v50, v94
	s_waitcnt vmcnt(11)
	ds_write_b32 v52, v95
	s_waitcnt vmcnt(10)
	ds_write_b32 v54, v96
	s_waitcnt vmcnt(9)
	ds_write_b32 v56, v97
	s_waitcnt vmcnt(8)
	ds_write_b32 v58, v98
	s_waitcnt vmcnt(7)
	ds_write_b32 v60, v99
	s_waitcnt vmcnt(6)
	ds_write_b32 v62, v100
	s_waitcnt vmcnt(5)
	ds_write_b32 v64, v101
	s_waitcnt vmcnt(4)
	ds_write_b32 v66, v102
	s_waitcnt vmcnt(3)
	ds_write_b32 v68, v103
	s_waitcnt vmcnt(2)
	ds_write_b32 v70, v104
	s_waitcnt vmcnt(1)
	ds_write_b32 v72, v105
	s_waitcnt vmcnt(0)
	ds_write_b32 v74, v106
	s_cbranch_scc1 .LBB0_71
	s_waitcnt lgkmcnt(0)
	ds_read2_b32 v[46:47], v5 offset0:33 offset1:41
	ds_read2_b32 v[48:49], v5 offset1:8
	ds_read2_b32 v[50:51], v5 offset0:66 offset1:74
	ds_read2_b32 v[52:53], v5 offset0:99 offset1:107
	ds_read2_b32 v[54:55], v5 offset0:132 offset1:140
	ds_read2_b32 v[56:57], v5 offset0:165 offset1:173
	ds_read2_b32 v[58:59], v5 offset0:198 offset1:206
	ds_read2_b32 v[60:61], v5 offset0:231 offset1:239
	s_lshl_b32 s26, s16, 1
	v_lshl_add_u64 v[62:63], v[24:25], 0, s[26:27]
	v_add_u32_e32 v8, s20, v3
	s_waitcnt lgkmcnt(6)
	v_cvt_pk_bf16_f32 v42, v48, v46
	s_waitcnt lgkmcnt(4)
	v_cvt_pk_bf16_f32 v43, v50, v52
	s_waitcnt lgkmcnt(2)
	v_cvt_pk_bf16_f32 v44, v54, v56
	s_waitcnt lgkmcnt(0)
	v_cvt_pk_bf16_f32 v45, v58, v60
	v_mad_u64_u32 v[64:65], s[16:17], v8, s22, v[62:63]
	global_store_dwordx4 v[64:65], v[42:45], off
	v_add_u32_e32 v8, s20, v7
	s_nop 0
	v_cvt_pk_bf16_f32 v42, v49, v47
	v_cvt_pk_bf16_f32 v43, v51, v53
	v_cvt_pk_bf16_f32 v44, v55, v57
	v_cvt_pk_bf16_f32 v45, v59, v61
	ds_read2_b32 v[48:49], v5 offset0:49 offset1:57
	ds_read2_b32 v[50:51], v5 offset0:16 offset1:24
	ds_read2_b32 v[52:53], v5 offset0:82 offset1:90
	ds_read2_b32 v[54:55], v5 offset0:115 offset1:123
	ds_read2_b32 v[56:57], v5 offset0:148 offset1:156
	ds_read2_b32 v[58:59], v5 offset0:181 offset1:189
	ds_read2_b32 v[60:61], v5 offset0:214 offset1:222
	ds_read2_b32 v[64:65], v5 offset0:247 offset1:255
	v_mad_u64_u32 v[46:47], s[16:17], v8, s22, v[62:63]
	v_add_u32_e32 v8, s20, v11
	global_store_dwordx4 v[46:47], v[42:45], off
	v_mad_u64_u32 v[46:47], s[16:17], v8, s22, v[62:63]
	s_waitcnt lgkmcnt(6)
	v_cvt_pk_bf16_f32 v42, v50, v48
	s_waitcnt lgkmcnt(4)
	v_cvt_pk_bf16_f32 v43, v52, v54
	s_waitcnt lgkmcnt(2)
	v_cvt_pk_bf16_f32 v44, v56, v58
	s_waitcnt lgkmcnt(0)
	v_cvt_pk_bf16_f32 v45, v60, v64
	v_add_u32_e32 v8, s20, v13
	global_store_dwordx4 v[46:47], v[42:45], off
	v_mad_u64_u32 v[46:47], s[16:17], v8, s22, v[62:63]
	s_nop 0
	v_cvt_pk_bf16_f32 v42, v51, v49
	v_cvt_pk_bf16_f32 v43, v53, v55
	v_cvt_pk_bf16_f32 v44, v57, v59
	v_cvt_pk_bf16_f32 v45, v61, v65
	global_store_dwordx4 v[46:47], v[42:45], off
	s_waitcnt lgkmcnt(0)

.LBB0_75:
	s_lshl_b32 s48, s21, 1
	s_lshl_b32 s49, s26, 1
	v_or_b32_e32 v8, s48, v1
	v_or_b32_e32 v76, s49, v4
	s_add_i32 s50, s48, 4
	s_add_i32 s51, s49, 4
	s_add_i32 s52, s48, 8
	s_add_i32 s53, s49, 8
	s_add_i32 s54, s48, 12
	s_add_i32 s55, s49, 12
	s_add_i32 s56, s48, 16
	s_add_i32 s57, s49, 16
	s_add_i32 s58, s48, 20
	s_add_i32 s59, s49, 20
	s_add_i32 s60, s48, 24
	s_add_i32 s61, s49, 24
	s_add_i32 s48, s48, 28
	s_add_i32 s49, s49, 28
	v_add_u32_e32 v44, s20, v76
	v_or_b32_e32 v77, s50, v1
	v_or_b32_e32 v78, s51, v4
	v_or_b32_e32 v79, s52, v1
	v_or_b32_e32 v80, s53, v4
	v_or_b32_e32 v81, s54, v1
	v_or_b32_e32 v82, s55, v4
	v_or_b32_e32 v83, s56, v1
	v_or_b32_e32 v84, s57, v4
	v_or_b32_e32 v85, s58, v1
	v_or_b32_e32 v86, s59, v4
	v_or_b32_e32 v87, s60, v1
	v_or_b32_e32 v88, s61, v4
	v_or_b32_e32 v89, s48, v1
	v_or_b32_e32 v90, s49, v4
	v_add_u32_e32 v46, s17, v8
	v_mad_i64_i32 v[44:45], s[48:49], v44, s28, v[42:43]
	v_add_u32_e32 v50, s17, v77
	v_add_u32_e32 v48, s20, v78
	v_add_u32_e32 v54, s17, v79
	v_add_u32_e32 v52, s20, v80
	v_add_u32_e32 v58, s17, v81
	v_add_u32_e32 v56, s20, v82
	v_add_u32_e32 v62, s17, v83
	v_add_u32_e32 v60, s20, v84
	v_add_u32_e32 v66, s17, v85
	v_add_u32_e32 v64, s20, v86
	v_add_u32_e32 v70, s17, v87
	v_add_u32_e32 v68, s20, v88
	v_add_u32_e32 v74, s17, v89
	v_add_u32_e32 v72, s20, v90
	v_mad_i64_i32 v[46:47], s[48:49], v46, s28, v[42:43]
	v_mad_i64_i32 v[48:49], s[48:49], v48, s28, v[42:43]
	v_mad_i64_i32 v[50:51], s[48:49], v50, s28, v[42:43]
	v_mad_i64_i32 v[52:53], s[48:49], v52, s28, v[42:43]
	v_mad_i64_i32 v[54:55], s[48:49], v54, s28, v[42:43]
	v_mad_i64_i32 v[56:57], s[48:49], v56, s28, v[42:43]
	v_mad_i64_i32 v[58:59], s[48:49], v58, s28, v[42:43]
	v_mad_i64_i32 v[60:61], s[48:49], v60, s28, v[42:43]
	v_mad_i64_i32 v[62:63], s[48:49], v62, s28, v[42:43]
	v_mad_i64_i32 v[64:65], s[48:49], v64, s28, v[42:43]
	v_mad_i64_i32 v[66:67], s[48:49], v66, s28, v[42:43]
	v_mad_i64_i32 v[68:69], s[48:49], v68, s28, v[42:43]
	v_mad_i64_i32 v[70:71], s[48:49], v70, s28, v[42:43]
	v_mad_i64_i32 v[72:73], s[48:49], v72, s28, v[42:43]
	v_mad_i64_i32 v[74:75], s[48:49], v74, s28, v[42:43]
	global_load_dword v91, v[44:45], off nt
	global_load_dword v92, v[46:47], off nt
	global_load_dword v93, v[48:49], off nt
	global_load_dword v94, v[50:51], off nt
	global_load_dword v95, v[52:53], off nt
	global_load_dword v96, v[54:55], off nt
	global_load_dword v97, v[56:57], off nt
	global_load_dword v98, v[58:59], off nt
	global_load_dword v99, v[60:61], off nt
	global_load_dword v100, v[62:63], off nt
	global_load_dword v101, v[64:65], off nt
	global_load_dword v102, v[66:67], off nt
	global_load_dword v103, v[68:69], off nt
	global_load_dword v104, v[70:71], off nt
	global_load_dword v105, v[72:73], off nt
	global_load_dword v106, v[74:75], off nt
	s_add_i32 s26, s26, 16
	s_add_i32 s21, s21, 16
	s_add_i32 s29, s29, -16
	v_mad_u64_u32 v[44:45], s[48:49], v76, s47, v[10:11]
	s_cmp_lg_u32 s29, 0
	v_mad_u64_u32 v[46:47], s[48:49], v8, s47, v[10:11]
	v_mad_u64_u32 v[48:49], s[48:49], v78, s47, v[10:11]
	v_mad_u64_u32 v[50:51], s[48:49], v77, s47, v[10:11]
	v_mad_u64_u32 v[52:53], s[48:49], v80, s47, v[10:11]
	v_mad_u64_u32 v[54:55], s[48:49], v79, s47, v[10:11]
	v_mad_u64_u32 v[56:57], s[48:49], v82, s47, v[10:11]
	v_mad_u64_u32 v[58:59], s[48:49], v81, s47, v[10:11]
	v_mad_u64_u32 v[60:61], s[48:49], v84, s47, v[10:11]
	v_mad_u64_u32 v[62:63], s[48:49], v83, s47, v[10:11]
	v_mad_u64_u32 v[64:65], s[48:49], v86, s47, v[10:11]
	v_mad_u64_u32 v[66:67], s[48:49], v85, s47, v[10:11]
	v_mad_u64_u32 v[68:69], s[48:49], v88, s47, v[10:11]
	v_mad_u64_u32 v[70:71], s[48:49], v87, s47, v[10:11]
	v_mad_u64_u32 v[72:73], s[48:49], v90, s47, v[10:11]
	v_mad_u64_u32 v[74:75], s[48:49], v89, s47, v[10:11]
	s_waitcnt vmcnt(15)
	ds_write_b32 v44, v91
	s_waitcnt vmcnt(14)
	ds_write_b32 v46, v92
	s_waitcnt vmcnt(13)
	ds_write_b32 v48, v93
	s_waitcnt vmcnt(12)
	ds_write_b32 v50, v94
	s_waitcnt vmcnt(11)
	ds_write_b32 v52, v95
	s_waitcnt vmcnt(10)
	ds_write_b32 v54, v96
	s_waitcnt vmcnt(9)
	ds_write_b32 v56, v97
	s_waitcnt vmcnt(8)
	ds_write_b32 v58, v98
	s_waitcnt vmcnt(7)
	ds_write_b32 v60, v99
	s_waitcnt vmcnt(6)
	ds_write_b32 v62, v100
	s_waitcnt vmcnt(5)
	ds_write_b32 v64, v101
	s_waitcnt vmcnt(4)
	ds_write_b32 v66, v102
	s_waitcnt vmcnt(3)
	ds_write_b32 v68, v103
	s_waitcnt vmcnt(2)
	ds_write_b32 v70, v104
	s_waitcnt vmcnt(1)
	ds_write_b32 v72, v105
	s_waitcnt vmcnt(0)
	ds_write_b32 v74, v106
	s_cbranch_scc1 .LBB0_75
	s_waitcnt lgkmcnt(0)
	ds_read2_b32 v[46:47], v5 offset0:33 offset1:41
	ds_read2_b32 v[48:49], v5 offset1:8
	ds_read2_b32 v[50:51], v5 offset0:66 offset1:74
	ds_read2_b32 v[52:53], v5 offset0:99 offset1:107
	ds_read2_b32 v[54:55], v5 offset0:132 offset1:140
	ds_read2_b32 v[56:57], v5 offset0:165 offset1:173
	ds_read2_b32 v[58:59], v5 offset0:198 offset1:206
	ds_read2_b32 v[60:61], v5 offset0:231 offset1:239
	v_or_b32_e32 v64, s16, v3
	s_ashr_i32 s21, s20, 31
	v_ashrrev_i32_e32 v65, 31, v64
	v_lshl_add_u64 v[62:63], s[20:21], 1, v[26:27]
	v_lshlrev_b64 v[64:65], 11, v[64:65]
	s_waitcnt lgkmcnt(6)
	v_cvt_pk_bf16_f32 v42, v48, v46
	s_waitcnt lgkmcnt(4)
	v_cvt_pk_bf16_f32 v43, v50, v52
	s_waitcnt lgkmcnt(2)
	v_cvt_pk_bf16_f32 v44, v54, v56
	s_waitcnt lgkmcnt(0)
	v_cvt_pk_bf16_f32 v45, v58, v60
	v_lshl_add_u64 v[64:65], v[62:63], 0, v[64:65]
	v_or_b32_e32 v46, s16, v7
	global_store_dwordx4 v[64:65], v[42:45], off
	s_nop 1
	v_cvt_pk_bf16_f32 v42, v49, v47
	v_ashrrev_i32_e32 v47, 31, v46
	v_cvt_pk_bf16_f32 v43, v51, v53
	v_cvt_pk_bf16_f32 v44, v55, v57
	v_cvt_pk_bf16_f32 v45, v59, v61
	v_lshlrev_b64 v[46:47], 11, v[46:47]
	ds_read2_b32 v[48:49], v5 offset0:49 offset1:57
	ds_read2_b32 v[50:51], v5 offset0:16 offset1:24
	ds_read2_b32 v[52:53], v5 offset0:82 offset1:90
	ds_read2_b32 v[54:55], v5 offset0:115 offset1:123
	ds_read2_b32 v[56:57], v5 offset0:148 offset1:156
	ds_read2_b32 v[58:59], v5 offset0:181 offset1:189
	ds_read2_b32 v[60:61], v5 offset0:214 offset1:222
	ds_read2_b32 v[64:65], v5 offset0:247 offset1:255
	v_lshl_add_u64 v[46:47], v[62:63], 0, v[46:47]
	global_store_dwordx4 v[46:47], v[42:45], off
	v_or_b32_e32 v46, s16, v11
	v_ashrrev_i32_e32 v47, 31, v46
	v_lshlrev_b64 v[46:47], 11, v[46:47]
	s_waitcnt lgkmcnt(6)
	v_cvt_pk_bf16_f32 v42, v50, v48
	s_waitcnt lgkmcnt(4)
	v_cvt_pk_bf16_f32 v43, v52, v54
	s_waitcnt lgkmcnt(2)
	v_cvt_pk_bf16_f32 v44, v56, v58
	s_waitcnt lgkmcnt(0)
	v_cvt_pk_bf16_f32 v45, v60, v64
	v_lshl_add_u64 v[46:47], v[62:63], 0, v[46:47]
	global_store_dwordx4 v[46:47], v[42:45], off
	v_or_b32_e32 v46, s16, v13
	v_ashrrev_i32_e32 v47, 31, v46
	v_lshlrev_b64 v[46:47], 11, v[46:47]
	v_cvt_pk_bf16_f32 v42, v51, v49
	v_cvt_pk_bf16_f32 v43, v53, v55
	v_cvt_pk_bf16_f32 v44, v57, v59
	v_cvt_pk_bf16_f32 v45, v61, v65
	v_lshl_add_u64 v[46:47], v[62:63], 0, v[46:47]
	global_store_dwordx4 v[46:47], v[42:45], off
	s_waitcnt lgkmcnt(0)
	s_branch .LBB0_22

.LBB0_79:
	global_load_dwordx4 v[14:17], v[8:9], off offset:-16 nt
	global_load_dwordx4 v[18:21], v[8:9], off nt
	v_lshl_add_u64 v[12:13], v[12:13], 0, s[14:15]
	v_cmp_lt_i64_e32 vcc, s[28:29], v[12:13]
	v_lshl_add_u64 v[8:9], v[8:9], 0, s[8:9]
	s_or_b64 s[26:27], vcc, s[26:27]
	s_waitcnt vmcnt(1)
	v_cvt_pk_bf16_f32 v14, v14, v15
	v_cvt_pk_bf16_f32 v15, v16, v17
	s_waitcnt vmcnt(0)
	v_cvt_pk_bf16_f32 v16, v18, v19
	v_cvt_pk_bf16_f32 v17, v20, v21
	global_store_dwordx4 v[10:11], v[14:17], off
	v_lshl_add_u64 v[10:11], v[10:11], 0, s[22:23]
	s_andn2_b64 exec, exec, s[26:27]
	s_cbranch_execnz .LBB0_79

.LBB0_82:
	global_load_dwordx4 v[14:17], v[8:9], off offset:-16 nt
	global_load_dwordx4 v[18:21], v[8:9], off nt
	v_lshl_add_u64 v[12:13], v[12:13], 0, s[14:15]
	v_cmp_lt_i64_e32 vcc, s[26:27], v[12:13]
	v_lshl_add_u64 v[8:9], v[8:9], 0, s[10:11]
	s_or_b64 s[22:23], vcc, s[22:23]
	s_waitcnt vmcnt(1)
	v_cvt_pk_bf16_f32 v14, v14, v15
	v_cvt_pk_bf16_f32 v15, v16, v17
	s_waitcnt vmcnt(0)
	v_cvt_pk_bf16_f32 v16, v18, v19
	v_cvt_pk_bf16_f32 v17, v20, v21
	global_store_dwordx4 v[10:11], v[14:17], off
	v_lshl_add_u64 v[10:11], v[10:11], 0, s[20:21]
	s_andn2_b64 exec, exec, s[22:23]
	s_cbranch_execnz .LBB0_82

.LBB0_106:
	global_load_dwordx4 v[10:13], v4, s[24:25] nt
	global_load_dwordx4 v[14:17], v4, s[24:25] offset:1024 nt
	global_load_dwordx4 v[18:21], v4, s[24:25] offset:2048 nt
	global_load_dwordx4 v[22:25], v4, s[24:25] offset:3072 nt
	s_lshr_b32 s18, s18, 4
	s_ashr_i32 s24, s6, 12
	s_add_i32 s18, s18, 8
	s_and_b64 s[20:21], s[20:21], exec
	s_cselect_b32 s18, s24, s18
	s_mul_hi_i32 s21, s18, 0x6000
	s_mulk_i32 s18, 0x6000
	s_add_u32 s20, s3, s18
	s_addc_u32 s21, s28, s21
	s_add_u32 s24, s20, 0x1000
	s_addc_u32 s25, s21, 0
	global_load_dwordx4 v[26:29], v4, s[24:25]
	global_load_dwordx4 v[30:33], v[0:1], off
	global_load_dwordx4 v[34:37], v4, s[20:21]
	s_lshl_b64 s[22:23], s[22:23], 11
	s_add_u32 s6, s6, s14
	s_addc_u32 s7, s7, s15
	s_add_u32 s8, s8, s16
	s_addc_u32 s9, s9, s17
	s_cmp_lt_i32 s6, 0x8200
	s_waitcnt vmcnt(6)
	v_mul_f32_e32 v9, v11, v11
	v_mul_f32_e32 v38, v13, v13
	s_waitcnt vmcnt(5)
	v_mul_f32_e32 v39, v15, v15
	v_mul_f32_e32 v40, v17, v17
	s_waitcnt vmcnt(4)
	v_mul_f32_e32 v41, v19, v19
	v_mul_f32_e32 v42, v21, v21
	v_fmac_f32_e32 v9, v10, v10
	v_fmac_f32_e32 v38, v12, v12
	v_fmac_f32_e32 v39, v14, v14
	v_fmac_f32_e32 v40, v16, v16
	s_waitcnt vmcnt(3)
	v_mul_f32_e32 v43, v23, v23
	v_mul_f32_e32 v44, v25, v25
	v_fmac_f32_e32 v41, v18, v18
	v_fmac_f32_e32 v42, v20, v20
	v_add_f32_e32 v9, v9, v38
	v_add_f32_e32 v38, v39, v40
	v_fmac_f32_e32 v43, v22, v22
	v_fmac_f32_e32 v44, v24, v24
	v_add_f32_e32 v39, v41, v42
	v_add_f32_e32 v9, v9, v38
	v_add_f32_e32 v40, v43, v44
	v_add_f32_e32 v9, v9, v39
	v_add_f32_e32 v9, v9, v40
	ds_swizzle_b32 v38, v9 offset:swizzle(SWAP,1)
	s_waitcnt vmcnt(2)
	v_pk_add_f32 v[28:29], v[28:29], 1.0 op_sel_hi:[1,0]
	v_pk_add_f32 v[26:27], v[26:27], 1.0 op_sel_hi:[1,0]
	v_lshl_add_u64 v[40:41], v[2:3], 0, s[22:23]
	s_waitcnt lgkmcnt(0)
	v_add_f32_e32 v9, v9, v38
	ds_swizzle_b32 v38, v9 offset:swizzle(SWAP,2)
	s_waitcnt lgkmcnt(0)
	v_add_f32_e32 v9, v9, v38
	ds_swizzle_b32 v38, v9 offset:swizzle(SWAP,4)
	s_waitcnt lgkmcnt(0)
	v_add_f32_e32 v9, v9, v38
	ds_swizzle_b32 v38, v9 offset:swizzle(SWAP,8)
	s_waitcnt lgkmcnt(0)
	v_add_f32_e32 v9, v9, v38
	ds_swizzle_b32 v38, v9 offset:swizzle(SWAP,16)
	s_waitcnt lgkmcnt(0)
	v_add_f32_e32 v9, v9, v38
	v_mov_b32_e32 v38, v9
	s_nop 1
	v_permlane32_swap_b32_e32 v9, v38
	v_add_f32_e32 v9, v9, v38
	v_fmamk_f32 v9, v9, 0x3a800000, v5
	v_rsq_f32_e32 v38, v9
	s_nop 0
	v_pk_mul_f32 v[12:13], v[12:13], v[38:39] op_sel_hi:[1,0]
	v_pk_mul_f32 v[10:11], v[10:11], v[38:39] op_sel_hi:[1,0]
	s_waitcnt vmcnt(1)
	v_pk_mul_f32 v[12:13], v[32:33], v[12:13]
	v_pk_mul_f32 v[10:11], v[30:31], v[10:11]
	s_waitcnt vmcnt(0)
	v_pk_fma_f32 v[12:13], v[28:29], v[12:13], v[36:37]
	v_pk_fma_f32 v[10:11], v[26:27], v[10:11], v[34:35]
	v_pk_mul_f32 v[16:17], v[16:17], v[38:39] op_sel_hi:[1,0]
	v_cvt_pk_bf16_f32 v10, v10, v11
	v_cvt_pk_bf16_f32 v11, v12, v13
	global_store_dwordx2 v[40:41], v[10:11], off
	global_load_dwordx4 v[10:13], v[0:1], off offset:1024
	s_nop 0
	global_load_dwordx4 v[26:29], v6, s[24:25]
	global_load_dwordx4 v[30:33], v4, s[20:21] offset:1024
	v_pk_mul_f32 v[14:15], v[14:15], v[38:39] op_sel_hi:[1,0]
	v_pk_mul_f32 v[20:21], v[20:21], v[38:39] op_sel_hi:[1,0]
	v_pk_mul_f32 v[18:19], v[18:19], v[38:39] op_sel_hi:[1,0]
	v_pk_mul_f32 v[24:25], v[24:25], v[38:39] op_sel_hi:[1,0]
	v_pk_mul_f32 v[22:23], v[22:23], v[38:39] op_sel_hi:[1,0]
	s_waitcnt vmcnt(2)
	v_pk_mul_f32 v[10:11], v[10:11], v[14:15]
	v_pk_mul_f32 v[12:13], v[12:13], v[16:17]
	s_waitcnt vmcnt(1)
	v_pk_add_f32 v[14:15], v[28:29], 1.0 op_sel_hi:[1,0]
	v_pk_add_f32 v[16:17], v[26:27], 1.0 op_sel_hi:[1,0]
	s_waitcnt vmcnt(0)
	v_pk_fma_f32 v[12:13], v[14:15], v[12:13], v[32:33]
	v_pk_fma_f32 v[10:11], v[16:17], v[10:11], v[30:31]
	s_nop 0
	v_cvt_pk_bf16_f32 v10, v10, v11
	v_cvt_pk_bf16_f32 v11, v12, v13
	global_store_dwordx2 v[40:41], v[10:11], off offset:512
	global_load_dwordx4 v[10:13], v[0:1], off offset:2048
	s_nop 0
	global_load_dwordx4 v[14:17], v7, s[24:25]
	global_load_dwordx4 v[26:29], v4, s[20:21] offset:2048
	s_waitcnt vmcnt(2)
	v_pk_mul_f32 v[10:11], v[18:19], v[10:11]
	v_pk_mul_f32 v[12:13], v[20:21], v[12:13]
	s_waitcnt vmcnt(1)
	v_pk_add_f32 v[16:17], v[16:17], 1.0 op_sel_hi:[1,0]
	v_pk_add_f32 v[14:15], v[14:15], 1.0 op_sel_hi:[1,0]
	s_waitcnt vmcnt(0)
	v_pk_fma_f32 v[12:13], v[12:13], v[16:17], v[28:29]
	v_pk_fma_f32 v[10:11], v[10:11], v[14:15], v[26:27]
	s_nop 0
	v_cvt_pk_bf16_f32 v10, v10, v11
	v_cvt_pk_bf16_f32 v11, v12, v13
	global_store_dwordx2 v[40:41], v[10:11], off offset:1024
	global_load_dwordx4 v[10:13], v[0:1], off offset:3072
	s_nop 0
	global_load_dwordx4 v[14:17], v8, s[24:25]
	global_load_dwordx4 v[18:21], v4, s[20:21] offset:3072
	s_waitcnt vmcnt(2)
	v_pk_mul_f32 v[10:11], v[22:23], v[10:11]
	v_pk_mul_f32 v[12:13], v[24:25], v[12:13]
	s_waitcnt vmcnt(1)
	v_pk_add_f32 v[16:17], v[16:17], 1.0 op_sel_hi:[1,0]
	v_pk_add_f32 v[14:15], v[14:15], 1.0 op_sel_hi:[1,0]
	s_waitcnt vmcnt(0)
	v_pk_fma_f32 v[12:13], v[12:13], v[16:17], v[20:21]
	v_pk_fma_f32 v[10:11], v[10:11], v[14:15], v[18:19]
	s_nop 0
	v_cvt_pk_bf16_f32 v10, v10, v11
	v_cvt_pk_bf16_f32 v11, v12, v13
	global_store_dwordx2 v[40:41], v[10:11], off offset:1536
	s_cbranch_scc0 .LBB0_111
